# rotated GEMM loops: s_nop pads between m0 write and LDS-DMA replaced by the independent delayed MFMA (7 sites)
# baseline (speedup 1.0000x reference)
; #define MFMA16(a, b, c) __builtin_amdgcn_mfma_f32_16x16x32_bf16((a), (b), (c), 0, 0, 0)
; DI bf16x8 ldfrag(const char* lds, int row, int chunk) { return *(const bf16x8*)(lds + swz(row, chunk)); }
; #define GEMM_SG1() do { __builtin_amdgcn_sched_group_barrier(0x100, 1, 0); __builtin_amdgcn_sched_group_barrier(0x008, 4, 0); } while (0)
; #define GEMM_SG2() do { __builtin_amdgcn_sched_group_barrier(0x100, 2, 0); __builtin_amdgcn_sched_group_barrier(0x008, 4, 0); } while (0)
; template <bool RSTD, bool SWAP>
; DI void gemm_tile(gacc_t& acc, const bf16_t* __restrict__ A, int lda, const bf16_t* __restrict__ Bt, int ldb, int K,
;                   char* lds, int tid, int wr, int wc, int lane, const float* ssq_row) {
;     ...
;     for (int kt = 0; kt < nk; ++kt) {
;         const char* cur = lds + (kt & 1) * 65536;
;         if (kt + 1 < nk) GEMM_ISSUE(kt + 1, (kt + 1) & 1);
;         bf16x8 bfr[2][4], afr[3];
; #pragma unroll
;         for (int n = 0; n < 4; ++n) bfr[0][n] = ldfrag(cur + 32768, wc * 64 + n * 16 + fr, fq);
;         afr[0] = ldfrag(cur, wr * 128 + fr, fq);
;         afr[1] = ldfrag(cur, wr * 128 + 16 + fr, fq);
; #pragma unroll
;         for (int idx = 0; idx < 16; ++idx) {
;             const int ks = idx >> 3, m = idx & 7;
;             if (idx < 14) afr[(idx + 2) % 3] = ldfrag(cur, wr * 128 + ((idx + 2) & 7) * 16 + fr, ((idx + 2) >> 3) * 4 + fq);
;             if (ks == 0 && m >= 2 && m < 6) bfr[1][m - 2] = ldfrag(cur + 32768, wc * 64 + (m - 2) * 16 + fr, 4 + fq);
; #pragma unroll
;             for (int n = 0; n < 4; ++n) acc[m][n] = SWAP ? MFMA16(bfr[ks][n], afr[idx % 3], acc[m][n]) : MFMA16(afr[idx % 3], bfr[ks][n], acc[m][n]);
;         }
;         __builtin_amdgcn_sched_group_barrier(0x100, 6, 0);
;     ...
;         GEMM_SG1(); GEMM_SG1(); GEMM_SG2(); GEMM_SG2(); GEMM_SG2(); GEMM_SG2(); GEMM_SG1(); GEMM_SG1();
;         GEMM_SG1(); GEMM_SG1(); GEMM_SG1(); GEMM_SG1(); GEMM_SG1(); GEMM_SG1();
;         __builtin_amdgcn_sched_group_barrier(0x008, 8, 0);
;         __builtin_amdgcn_sched_barrier(0);
;         asm volatile("s_waitcnt vmcnt(0)" ::: "memory");
;         __syncthreads();
.LBB0_141:
	s_add_i32 s30, s21, 0xffff0000
	s_and_b32 s31, s21, 0x10000
	v_lshl_add_u64 v[164:165], v[136:137], 0, s[6:7]
	s_and_b32 s34, s30, 0x10000
	s_add_i32 s35, s19, s31
	s_mov_b64 s[30:31], 0xc80080
	v_lshl_add_u64 v[172:173], v[164:165], 0, s[30:31]
	s_mov_b64 s[30:31], 0xca0080
	v_lshl_add_u64 v[176:177], v[164:165], 0, s[30:31]
	s_mov_b64 s[30:31], 0xcc0080
	v_lshl_add_u64 v[162:163], v[138:139], 0, s[6:7]
	v_lshl_add_u64 v[180:181], v[164:165], 0, s[30:31]
	s_mov_b64 s[30:31], 0xce0080
	v_lshl_add_u64 v[166:167], v[162:163], 0, s[94:95]
	v_lshl_add_u64 v[164:165], v[164:165], 0, s[30:31]
	s_add_i32 s31, s35, 0x8000
	s_mov_b32 m0, s35
	v_lshl_add_u64 v[174:175], v[162:163], 0, s[96:97]
	global_load_lds_dwordx4 v[166:167], off
	v_mfma_f32_16x16x32_bf16 v[60:63], v[210:213], v[236:239], v[60:63]
	s_mov_b32 m0, s31
	v_lshl_add_u64 v[178:179], v[162:163], 0, s[80:81]
	global_load_lds_dwordx4 v[172:173], off
	v_mfma_f32_16x16x32_bf16 v[56:59], v[214:217], v[236:239], v[56:59]
	s_add_i32 m0, s35, 0x2000
	v_lshl_add_u64 v[162:163], v[162:163], 0, s[82:83]
	global_load_lds_dwordx4 v[174:175], off
	v_mfma_f32_16x16x32_bf16 v[52:55], v[218:221], v[236:239], v[52:55]
	s_add_i32 m0, s35, 0xa000
	s_add_i32 s30, s34, 0
	global_load_lds_dwordx4 v[176:177], off
	v_mfma_f32_16x16x32_bf16 v[48:51], v[222:225], v[236:239], v[48:51]
	s_add_i32 m0, s35, 0x4000
	v_add_u32_e32 v146, s30, v143
	global_load_lds_dwordx4 v[178:179], off
	v_mfma_f32_16x16x32_bf16 v[44:47], v[210:213], v[240:243], v[44:47]
	s_add_i32 m0, s35, 0xc000
	v_add3_u32 v161, v146, v149, v150
	global_load_lds_dwordx4 v[180:181], off
	v_mfma_f32_16x16x32_bf16 v[40:43], v[214:217], v[240:243], v[40:43]
	s_add_i32 m0, s35, 0x6000
	v_add_u32_e32 v166, v146, v145
	global_load_lds_dwordx4 v[162:163], off
	v_mfma_f32_16x16x32_bf16 v[36:39], v[218:221], v[240:243], v[36:39]
	s_add_i32 m0, s35, 0xe000
	v_mfma_f32_16x16x32_bf16 v[32:35], v[222:225], v[240:243], v[32:35]
	global_load_lds_dwordx4 v[164:165], off
	ds_read_b128 v[162:165], v161 offset:32768
	ds_read_b128 v[186:189], v161 offset:34816
	ds_read_b128 v[194:197], v161 offset:36864
	ds_read_b128 v[198:201], v161 offset:38912
	ds_read_b128 v[190:193], v166
	ds_read_b128 v[202:205], v166 offset:2048
	v_add_u32_e32 v161, v146, v151
	ds_read_b128 v[206:209], v166 offset:4096
	v_mfma_f32_16x16x32_bf16 v[28:31], v[210:213], v[244:247], v[28:31]
	v_mfma_f32_16x16x32_bf16 v[24:27], v[214:217], v[244:247], v[24:27]
	v_mfma_f32_16x16x32_bf16 v[20:23], v[218:221], v[244:247], v[20:23]
	v_mfma_f32_16x16x32_bf16 v[16:19], v[222:225], v[244:247], v[16:19]
	v_mfma_f32_16x16x32_bf16 v[12:15], v[210:213], v[248:251], v[12:15]
	v_mfma_f32_16x16x32_bf16 v[8:11], v[214:217], v[248:251], v[8:11]
	v_mfma_f32_16x16x32_bf16 v[4:7], v[218:221], v[248:251], v[4:7]
	v_mfma_f32_16x16x32_bf16 v[0:3], v[222:225], v[248:251], v[0:3]
	s_waitcnt lgkmcnt(2)
	v_mfma_f32_16x16x32_bf16 v[124:127], v[162:165], v[190:193], v[124:127]
	v_add_u32_e32 v146, v146, v153
	v_mfma_f32_16x16x32_bf16 v[120:123], v[186:189], v[190:193], v[120:123]
	v_mfma_f32_16x16x32_bf16 v[116:119], v[194:197], v[190:193], v[116:119]
	v_mfma_f32_16x16x32_bf16 v[112:115], v[198:201], v[190:193], v[112:115]
	ds_read_b128 v[190:193], v161
	v_add_u32_e32 v161, s30, v148
	v_add_u32_e32 v167, v161, v152
	s_waitcnt lgkmcnt(2)
	v_mfma_f32_16x16x32_bf16 v[108:111], v[162:165], v[202:205], v[108:111]
	v_mfma_f32_16x16x32_bf16 v[104:107], v[186:189], v[202:205], v[104:107]
	v_mfma_f32_16x16x32_bf16 v[100:103], v[194:197], v[202:205], v[100:103]
	v_mfma_f32_16x16x32_bf16 v[96:99], v[198:201], v[202:205], v[96:99]
	ds_read_b128 v[202:205], v166 offset:8192
	ds_read_b128 v[210:213], v167 offset:32768
	s_waitcnt lgkmcnt(3)
	v_mfma_f32_16x16x32_bf16 v[92:95], v[162:165], v[206:209], v[92:95]
	v_mfma_f32_16x16x32_bf16 v[88:91], v[186:189], v[206:209], v[88:91]
	v_mfma_f32_16x16x32_bf16 v[84:87], v[194:197], v[206:209], v[84:87]
	v_mfma_f32_16x16x32_bf16 v[80:83], v[198:201], v[206:209], v[80:83]
	ds_read_b128 v[206:209], v166 offset:10240
	ds_read_b128 v[214:217], v167 offset:34816
	s_waitcnt lgkmcnt(4)
	v_mfma_f32_16x16x32_bf16 v[76:79], v[162:165], v[190:193], v[76:79]
	v_mfma_f32_16x16x32_bf16 v[72:75], v[186:189], v[190:193], v[72:75]
	v_mfma_f32_16x16x32_bf16 v[68:71], v[194:197], v[190:193], v[68:71]
	v_mfma_f32_16x16x32_bf16 v[64:67], v[198:201], v[190:193], v[64:67]
	ds_read_b128 v[190:193], v166 offset:12288
	v_add_u32_e32 v166, v161, v154
	ds_read_b128 v[218:221], v167 offset:36864
	s_waitcnt lgkmcnt(5)
	v_mfma_f32_16x16x32_bf16 v[60:63], v[162:165], v[202:205], v[60:63]
	v_mfma_f32_16x16x32_bf16 v[56:59], v[186:189], v[202:205], v[56:59]
	v_mfma_f32_16x16x32_bf16 v[52:55], v[194:197], v[202:205], v[52:55]
	v_mfma_f32_16x16x32_bf16 v[48:51], v[198:201], v[202:205], v[48:51]
	ds_read_b128 v[222:225], v166 offset:38912
	ds_read_b128 v[202:205], v146
	v_add_u32_e32 v146, v161, v145
	s_waitcnt lgkmcnt(5)
	v_mfma_f32_16x16x32_bf16 v[44:47], v[162:165], v[206:209], v[44:47]
	v_add_u32_e32 v166, v161, v151
	v_mfma_f32_16x16x32_bf16 v[40:43], v[186:189], v[206:209], v[40:43]
	v_mfma_f32_16x16x32_bf16 v[36:39], v[194:197], v[206:209], v[36:39]
	v_mfma_f32_16x16x32_bf16 v[32:35], v[198:201], v[206:209], v[32:35]
	ds_read_b128 v[206:209], v146
	s_waitcnt lgkmcnt(4)
	v_mfma_f32_16x16x32_bf16 v[28:31], v[162:165], v[190:193], v[28:31]
	v_mfma_f32_16x16x32_bf16 v[24:27], v[186:189], v[190:193], v[24:27]
	v_mfma_f32_16x16x32_bf16 v[20:23], v[194:197], v[190:193], v[20:23]
	v_mfma_f32_16x16x32_bf16 v[16:19], v[198:201], v[190:193], v[16:19]
	ds_read_b128 v[190:193], v146 offset:2048
	s_waitcnt lgkmcnt(2)
; #define MFMA16(a, b, c) __builtin_amdgcn_mfma_f32_16x16x32_bf16((a), (b), (c), 0, 0, 0)
; DI bf16x8 ldfrag(const char* lds, int row, int chunk) { return *(const bf16x8*)(lds + swz(row, chunk)); }
; #define GEMM_SG1() do { __builtin_amdgcn_sched_group_barrier(0x100, 1, 0); __builtin_amdgcn_sched_group_barrier(0x008, 4, 0); } while (0)
; #define GEMM_SG2() do { __builtin_amdgcn_sched_group_barrier(0x100, 2, 0); __builtin_amdgcn_sched_group_barrier(0x008, 4, 0); } while (0)
; template <bool RSTD, bool SWAP>
; DI void gemm_tile(gacc_t& acc, const bf16_t* __restrict__ A, int lda, const bf16_t* __restrict__ Bt, int ldb, int K,
;                   char* lds, int tid, int wr, int wc, int lane, const float* ssq_row) {
;     ...
;     for (int kt = 0; kt < nk; ++kt) {
;         const char* cur = lds + (kt & 1) * 65536;
;         if (kt + 1 < nk) GEMM_ISSUE(kt + 1, (kt + 1) & 1);
;         bf16x8 bfr[2][4], afr[3];
; #pragma unroll
;         for (int n = 0; n < 4; ++n) bfr[0][n] = ldfrag(cur + 32768, wc * 64 + n * 16 + fr, fq);
;         afr[0] = ldfrag(cur, wr * 128 + fr, fq);
;         afr[1] = ldfrag(cur, wr * 128 + 16 + fr, fq);
; #pragma unroll
;         for (int idx = 0; idx < 16; ++idx) {
;             const int ks = idx >> 3, m = idx & 7;
;             if (idx < 14) afr[(idx + 2) % 3] = ldfrag(cur, wr * 128 + ((idx + 2) & 7) * 16 + fr, ((idx + 2) >> 3) * 4 + fq);
;             if (ks == 0 && m >= 2 && m < 6) bfr[1][m - 2] = ldfrag(cur + 32768, wc * 64 + (m - 2) * 16 + fr, 4 + fq);
; #pragma unroll
;             for (int n = 0; n < 4; ++n) acc[m][n] = SWAP ? MFMA16(bfr[ks][n], afr[idx % 3], acc[m][n]) : MFMA16(afr[idx % 3], bfr[ks][n], acc[m][n]);
;         }
;         __builtin_amdgcn_sched_group_barrier(0x100, 6, 0);
;     ...
;         GEMM_SG1(); GEMM_SG1(); GEMM_SG2(); GEMM_SG2(); GEMM_SG2(); GEMM_SG2(); GEMM_SG1(); GEMM_SG1();
;         GEMM_SG1(); GEMM_SG1(); GEMM_SG1(); GEMM_SG1(); GEMM_SG1(); GEMM_SG1();
;         __builtin_amdgcn_sched_group_barrier(0x008, 8, 0);
;         __builtin_amdgcn_sched_barrier(0);
;         asm volatile("s_waitcnt vmcnt(0)" ::: "memory");
;         __syncthreads();
	v_mfma_f32_16x16x32_bf16 v[12:15], v[162:165], v[202:205], v[12:15]
	v_mfma_f32_16x16x32_bf16 v[8:11], v[186:189], v[202:205], v[8:11]
	v_mfma_f32_16x16x32_bf16 v[4:7], v[194:197], v[202:205], v[4:7]
	v_mfma_f32_16x16x32_bf16 v[0:3], v[198:201], v[202:205], v[0:3]
	ds_read_b128 v[162:165], v146 offset:4096
	s_waitcnt lgkmcnt(2)
	v_mfma_f32_16x16x32_bf16 v[124:127], v[210:213], v[206:209], v[124:127]
	v_mfma_f32_16x16x32_bf16 v[120:123], v[214:217], v[206:209], v[120:123]
	v_mfma_f32_16x16x32_bf16 v[116:119], v[218:221], v[206:209], v[116:119]
	v_mfma_f32_16x16x32_bf16 v[112:115], v[222:225], v[206:209], v[112:115]
	ds_read_b128 v[186:189], v166
	s_waitcnt lgkmcnt(2)
	v_mfma_f32_16x16x32_bf16 v[108:111], v[210:213], v[190:193], v[108:111]
	v_mfma_f32_16x16x32_bf16 v[104:107], v[214:217], v[190:193], v[104:107]
	v_mfma_f32_16x16x32_bf16 v[100:103], v[218:221], v[190:193], v[100:103]
	v_mfma_f32_16x16x32_bf16 v[96:99], v[222:225], v[190:193], v[96:99]
	ds_read_b128 v[236:239], v146 offset:8192
	s_waitcnt lgkmcnt(2)
	v_mfma_f32_16x16x32_bf16 v[92:95], v[210:213], v[162:165], v[92:95]
	v_mfma_f32_16x16x32_bf16 v[88:91], v[214:217], v[162:165], v[88:91]
	v_mfma_f32_16x16x32_bf16 v[84:87], v[218:221], v[162:165], v[84:87]
	v_mfma_f32_16x16x32_bf16 v[80:83], v[222:225], v[162:165], v[80:83]
	ds_read_b128 v[240:243], v146 offset:10240
	ds_read_b128 v[244:247], v146 offset:12288
	v_add_u32_e32 v146, v161, v153
	ds_read_b128 v[248:251], v146
	s_waitcnt lgkmcnt(4)
	v_mfma_f32_16x16x32_bf16 v[76:79], v[210:213], v[186:189], v[76:79]
	v_mfma_f32_16x16x32_bf16 v[72:75], v[214:217], v[186:189], v[72:75]
	v_mfma_f32_16x16x32_bf16 v[68:71], v[218:221], v[186:189], v[68:71]
	v_mfma_f32_16x16x32_bf16 v[64:67], v[222:225], v[186:189], v[64:67]
	s_waitcnt lgkmcnt(0)
	s_waitcnt vmcnt(0)
	s_add_u32 s6, s6, 0x80
	s_addc_u32 s7, s7, 0
	s_add_i32 s21, s21, 0x10000
	s_cmpk_lg_i32 s6, 0x780
	s_waitcnt vmcnt(0)
	s_cbranch_scc1 .Lkhead_141
	s_barrier
	v_mfma_f32_16x16x32_bf16 v[60:63], v[210:213], v[236:239], v[60:63]
	v_mfma_f32_16x16x32_bf16 v[56:59], v[214:217], v[236:239], v[56:59]
	v_mfma_f32_16x16x32_bf16 v[52:55], v[218:221], v[236:239], v[52:55]
	v_mfma_f32_16x16x32_bf16 v[48:51], v[222:225], v[236:239], v[48:51]
	v_mfma_f32_16x16x32_bf16 v[44:47], v[210:213], v[240:243], v[44:47]
	v_mfma_f32_16x16x32_bf16 v[40:43], v[214:217], v[240:243], v[40:43]
	v_mfma_f32_16x16x32_bf16 v[36:39], v[218:221], v[240:243], v[36:39]
	v_mfma_f32_16x16x32_bf16 v[32:35], v[222:225], v[240:243], v[32:35]
	v_mfma_f32_16x16x32_bf16 v[28:31], v[210:213], v[244:247], v[28:31]
	v_mfma_f32_16x16x32_bf16 v[24:27], v[214:217], v[244:247], v[24:27]
	v_mfma_f32_16x16x32_bf16 v[20:23], v[218:221], v[244:247], v[20:23]
	v_mfma_f32_16x16x32_bf16 v[16:19], v[222:225], v[244:247], v[16:19]
	v_mfma_f32_16x16x32_bf16 v[12:15], v[210:213], v[248:251], v[12:15]
	v_mfma_f32_16x16x32_bf16 v[8:11], v[214:217], v[248:251], v[8:11]
	v_mfma_f32_16x16x32_bf16 v[4:7], v[218:221], v[248:251], v[4:7]
	v_mfma_f32_16x16x32_bf16 v[0:3], v[222:225], v[248:251], v[0:3]
	ds_read_b128 v[136:139], v160
	ds_read_b128 v[162:165], v160 offset:2048
	ds_read_b128 v[190:193], v160 offset:4096
	ds_read_b128 v[194:197], v160 offset:6144
	v_add_u32_e32 v146, v155, v145
	ds_read_b128 v[186:189], v146
	ds_read_b128 v[198:201], v146 offset:2048
	ds_read_b128 v[202:205], v146 offset:4096
	s_waitcnt lgkmcnt(2)
	v_mfma_f32_16x16x32_bf16 v[124:127], v[136:139], v[186:189], v[124:127]
	v_mfma_f32_16x16x32_bf16 v[206:209], v[162:165], v[186:189], v[120:123]
	v_mfma_f32_16x16x32_bf16 v[116:119], v[190:193], v[186:189], v[116:119]
	v_mfma_f32_16x16x32_bf16 v[186:189], v[194:197], v[186:189], v[112:115]
	s_nop 2
	v_add_u32_e32 v112, v155, v151
	ds_read_b128 v[112:115], v112
	s_waitcnt lgkmcnt(2)
	v_mfma_f32_16x16x32_bf16 v[108:111], v[136:139], v[198:201], v[108:111]
	v_mfma_f32_16x16x32_bf16 v[210:213], v[162:165], v[198:201], v[104:107]
	v_mfma_f32_16x16x32_bf16 v[100:103], v[190:193], v[198:201], v[100:103]
	s_nop 1
	v_add_u32_e32 v104, v156, v152
	v_mfma_f32_16x16x32_bf16 v[198:201], v[194:197], v[198:201], v[96:99]
	ds_read_b128 v[214:217], v104
	s_nop 1
	ds_read_b128 v[96:99], v146 offset:8192
	s_waitcnt lgkmcnt(3)
	v_mfma_f32_16x16x32_bf16 v[92:95], v[136:139], v[202:205], v[92:95]
	v_mfma_f32_16x16x32_bf16 v[218:221], v[162:165], v[202:205], v[88:91]
	v_mfma_f32_16x16x32_bf16 v[84:87], v[190:193], v[202:205], v[84:87]
	v_mfma_f32_16x16x32_bf16 v[202:205], v[194:197], v[202:205], v[80:83]
	ds_read_b128 v[222:225], v104 offset:2048
	s_nop 1
	ds_read_b128 v[80:83], v146 offset:10240
	s_waitcnt lgkmcnt(4)
	v_mfma_f32_16x16x32_bf16 v[76:79], v[136:139], v[112:115], v[76:79]
	v_mfma_f32_16x16x32_bf16 v[226:229], v[162:165], v[112:115], v[72:75]
	v_mfma_f32_16x16x32_bf16 v[68:71], v[190:193], v[112:115], v[68:71]
	v_mfma_f32_16x16x32_bf16 v[230:233], v[194:197], v[112:115], v[64:67]
	ds_read_b128 v[234:237], v104 offset:4096
	s_nop 1
	ds_read_b128 v[64:67], v146 offset:12288
	s_waitcnt lgkmcnt(4)
	v_mfma_f32_16x16x32_bf16 v[238:241], v[162:165], v[96:99], v[56:59]
	v_mfma_f32_16x16x32_bf16 v[60:63], v[136:139], v[96:99], v[60:63]
	s_nop 1
	v_add_u32_e32 v56, v156, v154
	v_mfma_f32_16x16x32_bf16 v[52:55], v[190:193], v[96:99], v[52:55]
	v_mfma_f32_16x16x32_bf16 v[242:245], v[194:197], v[96:99], v[48:51]
	ds_read_b128 v[246:249], v56 offset:6144
	s_nop 1
	v_add_u32_e32 v48, v155, v153
	ds_read_b128 v[48:51], v48
	s_waitcnt lgkmcnt(4)
	v_mfma_f32_16x16x32_bf16 v[250:253], v[162:165], v[80:83], v[40:43]
	v_mfma_f32_16x16x32_bf16 v[44:47], v[136:139], v[80:83], v[44:47]
	s_nop 1
	v_add_u32_e32 v40, v157, v145
	v_mfma_f32_16x16x32_bf16 v[36:39], v[190:193], v[80:83], v[36:39]
	v_mfma_f32_16x16x32_bf16 v[172:175], v[194:197], v[80:83], v[32:35]
	s_nop 2
	ds_read_b128 v[32:35], v40
	s_waitcnt lgkmcnt(3)
; template <bool RSTD, bool SWAP>
; DI void gemm_tile(gacc_t& acc, const bf16_t* __restrict__ A, int lda, const bf16_t* __restrict__ Bt, int ldb, int K,
;                   char* lds, int tid, int wr, int wc, int lane, const float* ssq_row) {
;     ...
;         for (int idx = 0; idx < 16; ++idx) {
;             const int ks = idx >> 3, m = idx & 7;
;             if (idx < 14) afr[(idx + 2) % 3] = ldfrag(cur, wr * 128 + ((idx + 2) & 7) * 16 + fr, ((idx + 2) >> 3) * 4 + fq);
;             if (ks == 0 && m >= 2 && m < 6) bfr[1][m - 2] = ldfrag(cur + 32768, wc * 64 + (m - 2) * 16 + fr, 4 + fq);
; #pragma unroll
;             for (int n = 0; n < 4; ++n) acc[m][n] = SWAP ? MFMA16(bfr[ks][n], afr[idx % 3], acc[m][n]) : MFMA16(afr[idx % 3], bfr[ks][n], acc[m][n]);
;     DI void operator()(gacc_t& acc, int pm, int pn, char* lds, int tid, int wr, int wc, int lane) const {
;         asm volatile("" : "+v"(tid), "+v"(lane));
;         const int fr = lane & 15, fq = lane >> 4;
;         const int R0 = pm * 256;
;         const int t0 = R0 < TP ? (R0 & ~4095) : TP + ((R0 - TP) & ~8191);
;         const int S = R0 < TP ? 4096 : 8192;
;         char* lbase = lds + (wr * 128 + fr) * 528 + (wc * 64 + 4 * fq) * 2;
;         const float* rlt = (const float*)(lds + RSTD_OFF) + wr * 128 + fr;
;         if (pn < 8) {
;             const float sc = pn < 4 ? 0.18033688011112042f : 1.0f;
;             const f32x2* rbase = rope + (R0 - t0 + wr * 128 + fr) * 32 + 4 * fq;
; #pragma unroll
;             for (int m = 0; m < 8; ++m) {
;                 const float rs = rlt[m * 16] * sc;
; #pragma unroll
;                 for (int n = 0; n < 2; ++n) {
;                     const f32x4 c01 = *(const f32x4*)(rbase + m * 16 * 32 + n * 16), c23 = *(const f32x4*)(rbase + m * 16 * 32 + n * 16 + 2);
;                     const float cs_[4] = {c01.x, c01.z, c23.x, c23.z}, sn_[4] = {c01.y, c01.w, c23.y, c23.w};
;                     float o1[4], o2[4];
; #pragma unroll
;                     for (int j = 0; j < 4; ++j) {
;                         const float x1 = acc[m][n][j], x2 = acc[m][n + 2][j];
;                         o1[j] = (x1 * cs_[j] - x2 * sn_[j]) * rs; o2[j] = (x2 * cs_[j] + x1 * sn_[j]) * rs;
;                     }
;                     u32x2 w1, w2; w1.x = pk2(o1[0], o1[1]); w1.y = pk2(o1[2], o1[3]); w2.x = pk2(o2[0], o2[1]); w2.y = pk2(o2[2], o2[3]);
	v_mfma_f32_16x16x32_bf16 v[28:31], v[136:139], v[64:67], v[28:31]
	v_mfma_f32_16x16x32_bf16 v[176:179], v[162:165], v[64:67], v[24:27]
	v_mfma_f32_16x16x32_bf16 v[20:23], v[190:193], v[64:67], v[20:23]
	v_mfma_f32_16x16x32_bf16 v[180:183], v[194:197], v[64:67], v[16:19]
	s_nop 2
	ds_read_b128 v[16:19], v40 offset:2048
	s_waitcnt lgkmcnt(2)
	v_mfma_f32_16x16x32_bf16 v[12:15], v[136:139], v[48:51], v[12:15]
	v_mfma_f32_16x16x32_bf16 v[136:139], v[162:165], v[48:51], v[8:11]
	s_nop 2
	v_add_u32_e32 v8, v157, v151
	v_mfma_f32_16x16x32_bf16 v[4:7], v[190:193], v[48:51], v[4:7]
	v_mfma_f32_16x16x32_bf16 v[162:165], v[194:197], v[48:51], v[0:3]
	s_nop 2
	ds_read_b128 v[0:3], v40 offset:4096
	s_waitcnt lgkmcnt(2)
	v_mfma_f32_16x16x32_bf16 v[120:123], v[214:217], v[32:35], v[124:127]
	v_mfma_f32_16x16x32_bf16 v[112:115], v[222:225], v[32:35], v[206:209]
	v_mfma_f32_16x16x32_bf16 v[124:127], v[234:237], v[32:35], v[116:119]
	v_mfma_f32_16x16x32_bf16 v[116:119], v[246:249], v[32:35], v[186:189]
	ds_read_b128 v[8:11], v8
	s_waitcnt lgkmcnt(2)
	v_mfma_f32_16x16x32_bf16 v[104:107], v[214:217], v[16:19], v[108:111]
	v_mfma_f32_16x16x32_bf16 v[96:99], v[222:225], v[16:19], v[210:213]
	v_mfma_f32_16x16x32_bf16 v[108:111], v[234:237], v[16:19], v[100:103]
	v_mfma_f32_16x16x32_bf16 v[100:103], v[246:249], v[16:19], v[198:201]
	ds_read_b128 v[16:19], v40 offset:8192
	s_waitcnt lgkmcnt(2)
	v_mfma_f32_16x16x32_bf16 v[88:91], v[214:217], v[0:3], v[92:95]
	v_mfma_f32_16x16x32_bf16 v[80:83], v[222:225], v[0:3], v[218:221]
	v_mfma_f32_16x16x32_bf16 v[92:95], v[234:237], v[0:3], v[84:87]
	v_mfma_f32_16x16x32_bf16 v[84:87], v[246:249], v[0:3], v[202:205]
	ds_read_b128 v[0:3], v40 offset:10240
	s_waitcnt lgkmcnt(2)
	v_mfma_f32_16x16x32_bf16 v[72:75], v[214:217], v[8:11], v[76:79]
	v_mfma_f32_16x16x32_bf16 v[64:67], v[222:225], v[8:11], v[226:229]
	v_mfma_f32_16x16x32_bf16 v[76:79], v[234:237], v[8:11], v[68:71]
	v_mfma_f32_16x16x32_bf16 v[68:71], v[246:249], v[8:11], v[230:233]
	ds_read_b128 v[8:11], v40 offset:12288
	s_waitcnt lgkmcnt(2)
	v_mfma_f32_16x16x32_bf16 v[56:59], v[214:217], v[16:19], v[60:63]
	v_mfma_f32_16x16x32_bf16 v[48:51], v[222:225], v[16:19], v[238:241]
	v_mfma_f32_16x16x32_bf16 v[60:63], v[234:237], v[16:19], v[52:55]
	v_mfma_f32_16x16x32_bf16 v[52:55], v[246:249], v[16:19], v[242:245]
	v_add_u32_e32 v16, v157, v153
	ds_read_b128 v[186:189], v16
	s_waitcnt lgkmcnt(2)
	v_mfma_f32_16x16x32_bf16 v[40:43], v[214:217], v[0:3], v[44:47]
	v_mfma_f32_16x16x32_bf16 v[32:35], v[222:225], v[0:3], v[250:253]
	v_mfma_f32_16x16x32_bf16 v[44:47], v[234:237], v[0:3], v[36:39]
	v_mfma_f32_16x16x32_bf16 v[36:39], v[246:249], v[0:3], v[172:175]
	s_waitcnt lgkmcnt(1)
	v_mfma_f32_16x16x32_bf16 v[24:27], v[214:217], v[8:11], v[28:31]
	v_mfma_f32_16x16x32_bf16 v[16:19], v[222:225], v[8:11], v[176:179]
	v_mfma_f32_16x16x32_bf16 v[28:31], v[234:237], v[8:11], v[20:23]
	v_mfma_f32_16x16x32_bf16 v[20:23], v[246:249], v[8:11], v[180:183]
	s_waitcnt lgkmcnt(0)
	v_mfma_f32_16x16x32_bf16 v[8:11], v[214:217], v[186:189], v[12:15]
	v_mfma_f32_16x16x32_bf16 v[0:3], v[222:225], v[186:189], v[136:139]
	v_mfma_f32_16x16x32_bf16 v[12:15], v[234:237], v[186:189], v[4:7]
	v_mfma_f32_16x16x32_bf16 v[4:7], v[246:249], v[186:189], v[162:165]
	s_nop 0
	v_mov_b32_e32 v138, v140
	v_mov_b32_e32 v136, v141
	s_cmp_lt_i32 s20, 64
	s_waitcnt vmcnt(0)
	s_barrier
	s_cselect_b64 s[6:7], -1, 0
	v_and_b32_e32 v137, 15, v136
	s_and_b64 s[20:21], s[6:7], exec
	s_movk_i32 s19, 0xf000
	v_ashrrev_i32_e32 v136, 2, v136
	s_cselect_b32 s19, s19, 0x7fffe000
	v_or_b32_e32 v139, v137, v144
	v_and_b32_e32 v136, -4, v136
	s_ashr_i32 s17, s17, 24
	v_mul_lo_u32 v139, v139, s3
	v_lshlrev_b32_e32 v146, 1, v136
	s_cmp_gt_i32 s17, 7
	v_add3_u32 v139, v158, v139, v146
	v_lshl_add_u32 v146, v137, 2, v159
	s_cselect_b64 s[20:21], -1, 0
	s_cmp_lt_i32 s17, 8
	s_mov_b64 s[30:31], -1
	s_cbranch_scc1 .LBB0_144
	ds_read_b32 v162, v146
	v_add_u32_e32 v161, 0x2000, v139
	s_mov_b64 s[30:31], 0
	s_waitcnt lgkmcnt(0)
	v_pk_mul_f32 v[164:165], v[120:121], v[162:163] op_sel_hi:[1,0]
	v_pk_mul_f32 v[166:167], v[122:123], v[162:163] op_sel_hi:[1,0]
	v_cvt_pk_bf16_f32 v164, v164, v165
	v_cvt_pk_bf16_f32 v165, v166, v167
	v_pk_mul_f32 v[166:167], v[112:113], v[162:163] op_sel_hi:[1,0]
	v_pk_mul_f32 v[172:173], v[114:115], v[162:163] op_sel_hi:[1,0]
	v_cvt_pk_bf16_f32 v166, v166, v167
	v_cvt_pk_bf16_f32 v167, v172, v173
	ds_write2_b64 v139, v[164:165], v[166:167] offset1:4
	v_pk_mul_f32 v[164:165], v[124:125], v[162:163] op_sel_hi:[1,0]
	v_pk_mul_f32 v[166:167], v[126:127], v[162:163] op_sel_hi:[1,0]
	v_cvt_pk_bf16_f32 v164, v164, v165
	v_cvt_pk_bf16_f32 v165, v166, v167
	v_pk_mul_f32 v[166:167], v[116:117], v[162:163] op_sel_hi:[1,0]
	v_pk_mul_f32 v[162:163], v[118:119], v[162:163] op_sel_hi:[1,0]
	v_cvt_pk_bf16_f32 v166, v166, v167
	v_cvt_pk_bf16_f32 v167, v162, v163
	ds_write2_b64 v139, v[164:165], v[166:167] offset0:8 offset1:12
	ds_read_b32 v162, v146 offset:64
	s_waitcnt lgkmcnt(0)
	v_pk_mul_f32 v[164:165], v[104:105], v[162:163] op_sel_hi:[1,0]
	v_pk_mul_f32 v[166:167], v[106:107], v[162:163] op_sel_hi:[1,0]
	v_cvt_pk_bf16_f32 v164, v164, v165
	v_cvt_pk_bf16_f32 v165, v166, v167
	v_pk_mul_f32 v[166:167], v[96:97], v[162:163] op_sel_hi:[1,0]
	v_pk_mul_f32 v[172:173], v[98:99], v[162:163] op_sel_hi:[1,0]
	v_cvt_pk_bf16_f32 v166, v166, v167
	v_cvt_pk_bf16_f32 v167, v172, v173
	ds_write2_b64 v161, v[164:165], v[166:167] offset0:32 offset1:36
	v_pk_mul_f32 v[164:165], v[108:109], v[162:163] op_sel_hi:[1,0]
	v_pk_mul_f32 v[166:167], v[110:111], v[162:163] op_sel_hi:[1,0]
	v_cvt_pk_bf16_f32 v164, v164, v165
	v_cvt_pk_bf16_f32 v165, v166, v167
	v_pk_mul_f32 v[166:167], v[100:101], v[162:163] op_sel_hi:[1,0]
	v_pk_mul_f32 v[162:163], v[102:103], v[162:163] op_sel_hi:[1,0]
	v_cvt_pk_bf16_f32 v166, v166, v167
	v_cvt_pk_bf16_f32 v167, v162, v163
	ds_write2_b64 v161, v[164:165], v[166:167] offset0:40 offset1:44
	ds_read_b32 v162, v146 offset:128
	v_add_u32_e32 v161, 0x4000, v139
	s_waitcnt lgkmcnt(0)
; DI unsigned pk2(float a, float b) { f32x2 v = {a, b}; bf16x2_t r = __builtin_convertvector(v, bf16x2_t); return __builtin_bit_cast(unsigned, r); }
;     DI void operator()(gacc_t& acc, int pm, int pn, char* lds, int tid, int wr, int wc, int lane) const {
;     ...
; #pragma unroll
;             for (int m = 0; m < 8; ++m) {
;                 const float r = rlt[m * 16];
; #pragma unroll
;                 for (int n = 0; n < 4; ++n) { u32x2 w; w.x = pk2(acc[m][n][0] * r, acc[m][n][1] * r); w.y = pk2(acc[m][n][2] * r, acc[m][n][3] * r); *(u32x2*)(lbase + m * 16 * 528 + n * 32) = w; }
;             }
	v_pk_mul_f32 v[164:165], v[88:89], v[162:163] op_sel_hi:[1,0]
	v_pk_mul_f32 v[166:167], v[90:91], v[162:163] op_sel_hi:[1,0]
	v_cvt_pk_bf16_f32 v164, v164, v165
	v_cvt_pk_bf16_f32 v165, v166, v167
	v_pk_mul_f32 v[166:167], v[80:81], v[162:163] op_sel_hi:[1,0]
	v_pk_mul_f32 v[172:173], v[82:83], v[162:163] op_sel_hi:[1,0]
	v_cvt_pk_bf16_f32 v166, v166, v167
	v_cvt_pk_bf16_f32 v167, v172, v173
	ds_write2_b64 v161, v[164:165], v[166:167] offset0:64 offset1:68
	v_pk_mul_f32 v[164:165], v[92:93], v[162:163] op_sel_hi:[1,0]
	v_pk_mul_f32 v[166:167], v[94:95], v[162:163] op_sel_hi:[1,0]
	v_cvt_pk_bf16_f32 v164, v164, v165
	v_cvt_pk_bf16_f32 v165, v166, v167
	v_pk_mul_f32 v[166:167], v[84:85], v[162:163] op_sel_hi:[1,0]
	v_pk_mul_f32 v[162:163], v[86:87], v[162:163] op_sel_hi:[1,0]
	v_cvt_pk_bf16_f32 v166, v166, v167
	v_cvt_pk_bf16_f32 v167, v162, v163
	ds_write2_b64 v161, v[164:165], v[166:167] offset0:72 offset1:76
	ds_read_b32 v162, v146 offset:192
	v_add_u32_e32 v161, 0x6000, v139
	s_waitcnt lgkmcnt(0)
	v_pk_mul_f32 v[164:165], v[72:73], v[162:163] op_sel_hi:[1,0]
	v_pk_mul_f32 v[166:167], v[74:75], v[162:163] op_sel_hi:[1,0]
	v_cvt_pk_bf16_f32 v164, v164, v165
	v_cvt_pk_bf16_f32 v165, v166, v167
	v_pk_mul_f32 v[166:167], v[64:65], v[162:163] op_sel_hi:[1,0]
	v_pk_mul_f32 v[172:173], v[66:67], v[162:163] op_sel_hi:[1,0]
	v_cvt_pk_bf16_f32 v166, v166, v167
	v_cvt_pk_bf16_f32 v167, v172, v173
	ds_write2_b64 v161, v[164:165], v[166:167] offset0:96 offset1:100
	v_pk_mul_f32 v[164:165], v[76:77], v[162:163] op_sel_hi:[1,0]
	v_pk_mul_f32 v[166:167], v[78:79], v[162:163] op_sel_hi:[1,0]
	v_cvt_pk_bf16_f32 v164, v164, v165
	v_cvt_pk_bf16_f32 v165, v166, v167
	v_pk_mul_f32 v[166:167], v[68:69], v[162:163] op_sel_hi:[1,0]
	v_pk_mul_f32 v[162:163], v[70:71], v[162:163] op_sel_hi:[1,0]
	v_cvt_pk_bf16_f32 v166, v166, v167
	v_cvt_pk_bf16_f32 v167, v162, v163
	ds_write2_b64 v161, v[164:165], v[166:167] offset0:104 offset1:108
	ds_read_b32 v162, v146 offset:256
	v_add_u32_e32 v161, 0x8000, v139
	s_waitcnt lgkmcnt(0)
	v_pk_mul_f32 v[164:165], v[56:57], v[162:163] op_sel_hi:[1,0]
	v_pk_mul_f32 v[166:167], v[58:59], v[162:163] op_sel_hi:[1,0]
	v_cvt_pk_bf16_f32 v164, v164, v165
	v_cvt_pk_bf16_f32 v165, v166, v167
	v_pk_mul_f32 v[166:167], v[48:49], v[162:163] op_sel_hi:[1,0]
	v_pk_mul_f32 v[172:173], v[50:51], v[162:163] op_sel_hi:[1,0]
	v_cvt_pk_bf16_f32 v166, v166, v167
	v_cvt_pk_bf16_f32 v167, v172, v173
	ds_write2_b64 v161, v[164:165], v[166:167] offset0:128 offset1:132
	v_pk_mul_f32 v[164:165], v[60:61], v[162:163] op_sel_hi:[1,0]
	v_pk_mul_f32 v[166:167], v[62:63], v[162:163] op_sel_hi:[1,0]
	v_cvt_pk_bf16_f32 v164, v164, v165
	v_cvt_pk_bf16_f32 v165, v166, v167
	v_pk_mul_f32 v[166:167], v[52:53], v[162:163] op_sel_hi:[1,0]
	v_pk_mul_f32 v[162:163], v[54:55], v[162:163] op_sel_hi:[1,0]
	v_cvt_pk_bf16_f32 v166, v166, v167
	v_cvt_pk_bf16_f32 v167, v162, v163
	ds_write2_b64 v161, v[164:165], v[166:167] offset0:136 offset1:140
	ds_read_b32 v162, v146 offset:320
	v_add_u32_e32 v161, 0xa000, v139
	s_waitcnt lgkmcnt(0)
	v_pk_mul_f32 v[164:165], v[40:41], v[162:163] op_sel_hi:[1,0]
	v_pk_mul_f32 v[166:167], v[42:43], v[162:163] op_sel_hi:[1,0]
	v_cvt_pk_bf16_f32 v164, v164, v165
	v_cvt_pk_bf16_f32 v165, v166, v167
	v_pk_mul_f32 v[166:167], v[32:33], v[162:163] op_sel_hi:[1,0]
	v_pk_mul_f32 v[172:173], v[34:35], v[162:163] op_sel_hi:[1,0]
	v_cvt_pk_bf16_f32 v166, v166, v167
	v_cvt_pk_bf16_f32 v167, v172, v173
	ds_write2_b64 v161, v[164:165], v[166:167] offset0:160 offset1:164
	v_pk_mul_f32 v[164:165], v[44:45], v[162:163] op_sel_hi:[1,0]
	v_pk_mul_f32 v[166:167], v[46:47], v[162:163] op_sel_hi:[1,0]
	v_cvt_pk_bf16_f32 v164, v164, v165
	v_cvt_pk_bf16_f32 v165, v166, v167
	v_pk_mul_f32 v[166:167], v[36:37], v[162:163] op_sel_hi:[1,0]
	v_pk_mul_f32 v[162:163], v[38:39], v[162:163] op_sel_hi:[1,0]
	v_cvt_pk_bf16_f32 v166, v166, v167
	v_cvt_pk_bf16_f32 v167, v162, v163
	ds_write2_b64 v161, v[164:165], v[166:167] offset0:168 offset1:172
	ds_read_b32 v162, v146 offset:384
	v_add_u32_e32 v161, 0xc000, v139
	s_waitcnt lgkmcnt(0)
	v_pk_mul_f32 v[164:165], v[24:25], v[162:163] op_sel_hi:[1,0]
	v_pk_mul_f32 v[166:167], v[26:27], v[162:163] op_sel_hi:[1,0]
	v_cvt_pk_bf16_f32 v164, v164, v165
	v_cvt_pk_bf16_f32 v165, v166, v167
	v_pk_mul_f32 v[166:167], v[16:17], v[162:163] op_sel_hi:[1,0]
	v_pk_mul_f32 v[172:173], v[18:19], v[162:163] op_sel_hi:[1,0]
	v_cvt_pk_bf16_f32 v166, v166, v167
	v_cvt_pk_bf16_f32 v167, v172, v173
	ds_write2_b64 v161, v[164:165], v[166:167] offset0:192 offset1:196
	v_pk_mul_f32 v[164:165], v[28:29], v[162:163] op_sel_hi:[1,0]
	v_pk_mul_f32 v[166:167], v[30:31], v[162:163] op_sel_hi:[1,0]
	v_cvt_pk_bf16_f32 v164, v164, v165
	v_cvt_pk_bf16_f32 v165, v166, v167
	v_pk_mul_f32 v[166:167], v[20:21], v[162:163] op_sel_hi:[1,0]
	v_pk_mul_f32 v[162:163], v[22:23], v[162:163] op_sel_hi:[1,0]
	v_cvt_pk_bf16_f32 v166, v166, v167
	v_cvt_pk_bf16_f32 v167, v162, v163
	ds_write2_b64 v161, v[164:165], v[166:167] offset0:200 offset1:204
	ds_read_b32 v162, v146 offset:448
	v_add_u32_e32 v161, 0xe000, v139
	s_waitcnt lgkmcnt(0)
	v_pk_mul_f32 v[164:165], v[8:9], v[162:163] op_sel_hi:[1,0]
	v_pk_mul_f32 v[166:167], v[10:11], v[162:163] op_sel_hi:[1,0]
	v_cvt_pk_bf16_f32 v164, v164, v165
	v_cvt_pk_bf16_f32 v165, v166, v167
	v_pk_mul_f32 v[166:167], v[0:1], v[162:163] op_sel_hi:[1,0]
	v_pk_mul_f32 v[172:173], v[2:3], v[162:163] op_sel_hi:[1,0]
	v_cvt_pk_bf16_f32 v166, v166, v167
	v_cvt_pk_bf16_f32 v167, v172, v173
	ds_write2_b64 v161, v[164:165], v[166:167] offset0:224 offset1:228
	v_pk_mul_f32 v[164:165], v[12:13], v[162:163] op_sel_hi:[1,0]
	v_pk_mul_f32 v[166:167], v[14:15], v[162:163] op_sel_hi:[1,0]
	v_cvt_pk_bf16_f32 v164, v164, v165
	v_cvt_pk_bf16_f32 v165, v166, v167
	v_pk_mul_f32 v[166:167], v[4:5], v[162:163] op_sel_hi:[1,0]
	v_pk_mul_f32 v[162:163], v[6:7], v[162:163] op_sel_hi:[1,0]
	v_cvt_pk_bf16_f32 v166, v166, v167
	v_cvt_pk_bf16_f32 v167, v162, v163
	ds_write2_b64 v161, v[164:165], v[166:167] offset0:232 offset1:236

; #define MFMA16(a, b, c) __builtin_amdgcn_mfma_f32_16x16x32_bf16((a), (b), (c), 0, 0, 0)
; DI bf16x8 ldfrag(const char* lds, int row, int chunk) { return *(const bf16x8*)(lds + swz(row, chunk)); }
; #define GEMM_SG1() do { __builtin_amdgcn_sched_group_barrier(0x100, 1, 0); __builtin_amdgcn_sched_group_barrier(0x008, 4, 0); } while (0)
; #define GEMM_SG2() do { __builtin_amdgcn_sched_group_barrier(0x100, 2, 0); __builtin_amdgcn_sched_group_barrier(0x008, 4, 0); } while (0)
; template <bool RSTD, bool SWAP>
; DI void gemm_tile(gacc_t& acc, const bf16_t* __restrict__ A, int lda, const bf16_t* __restrict__ Bt, int ldb, int K,
;                   char* lds, int tid, int wr, int wc, int lane, const float* ssq_row) {
;     ...
;     for (int kt = 0; kt < nk; ++kt) {
;         const char* cur = lds + (kt & 1) * 65536;
;         if (kt + 1 < nk) GEMM_ISSUE(kt + 1, (kt + 1) & 1);
;         bf16x8 bfr[2][4], afr[3];
; #pragma unroll
;         for (int n = 0; n < 4; ++n) bfr[0][n] = ldfrag(cur + 32768, wc * 64 + n * 16 + fr, fq);
;         afr[0] = ldfrag(cur, wr * 128 + fr, fq);
;         afr[1] = ldfrag(cur, wr * 128 + 16 + fr, fq);
; #pragma unroll
;         for (int idx = 0; idx < 16; ++idx) {
;             const int ks = idx >> 3, m = idx & 7;
;             if (idx < 14) afr[(idx + 2) % 3] = ldfrag(cur, wr * 128 + ((idx + 2) & 7) * 16 + fr, ((idx + 2) >> 3) * 4 + fq);
;             if (ks == 0 && m >= 2 && m < 6) bfr[1][m - 2] = ldfrag(cur + 32768, wc * 64 + (m - 2) * 16 + fr, 4 + fq);
; #pragma unroll
;             for (int n = 0; n < 4; ++n) acc[m][n] = SWAP ? MFMA16(bfr[ks][n], afr[idx % 3], acc[m][n]) : MFMA16(afr[idx % 3], bfr[ks][n], acc[m][n]);
;         }
;         __builtin_amdgcn_sched_group_barrier(0x100, 6, 0);
;     ...
;         GEMM_SG1(); GEMM_SG1(); GEMM_SG2(); GEMM_SG2(); GEMM_SG2(); GEMM_SG2(); GEMM_SG1(); GEMM_SG1();
;         GEMM_SG1(); GEMM_SG1(); GEMM_SG1(); GEMM_SG1(); GEMM_SG1(); GEMM_SG1();
;         __builtin_amdgcn_sched_group_barrier(0x008, 8, 0);
;         __builtin_amdgcn_sched_barrier(0);
;         asm volatile("s_waitcnt vmcnt(0)" ::: "memory");
;         __syncthreads();
.LBB0_281:
	v_lshl_add_u64 v[158:159], v[136:137], 0, s[4:5]
	s_mov_b64 s[20:21], 0x1880080
	v_lshl_add_u64 v[162:163], v[158:159], 0, s[20:21]
	s_mov_b64 s[20:21], 0x18a0080
	s_add_i32 s18, s17, 0xffff0000
	s_and_b32 s19, s17, 0x10000
	v_lshl_add_u64 v[166:167], v[158:159], 0, s[20:21]
	s_mov_b64 s[20:21], 0x18c0080
	s_and_b32 s23, s18, 0x10000
	s_add_i32 s18, s19, 0
	v_lshl_add_u64 v[174:175], v[158:159], 0, s[20:21]
	s_mov_b64 s[20:21], 0x18e0080
	v_lshl_add_u64 v[156:157], v[138:139], 0, s[4:5]
	v_lshl_add_u64 v[158:159], v[158:159], 0, s[20:21]
	s_add_i32 s20, s18, s16
	v_lshl_add_u64 v[160:161], v[156:157], 0, s[14:15]
	s_add_i32 s21, s20, 0x8000
	s_mov_b32 m0, s20
	v_lshl_add_u64 v[164:165], v[156:157], 0, s[72:73]
	global_load_lds_dwordx4 v[160:161], off
	v_mfma_f32_16x16x32_bf16 v[60:63], v[194:197], v[236:239], v[60:63]
	s_mov_b32 m0, s21
	v_lshl_add_u64 v[172:173], v[156:157], 0, s[76:77]
	global_load_lds_dwordx4 v[162:163], off
	v_mfma_f32_16x16x32_bf16 v[56:59], v[198:201], v[236:239], v[56:59]
	s_add_i32 m0, s20, 0x2000
	v_lshl_add_u64 v[156:157], v[156:157], 0, s[0:1]
	global_load_lds_dwordx4 v[164:165], off
	v_mfma_f32_16x16x32_bf16 v[52:55], v[202:205], v[236:239], v[52:55]
	s_add_i32 m0, s20, 0xa000
	s_add_i32 s19, s23, 0
	global_load_lds_dwordx4 v[166:167], off
	v_mfma_f32_16x16x32_bf16 v[48:51], v[206:209], v[236:239], v[48:51]
	s_add_i32 m0, s20, 0x4000
	v_add_u32_e32 v146, s19, v142
	global_load_lds_dwordx4 v[172:173], off
	v_mfma_f32_16x16x32_bf16 v[44:47], v[194:197], v[240:243], v[44:47]
	s_add_i32 m0, s20, 0xc000
	v_add3_u32 v155, v146, v148, v149
	global_load_lds_dwordx4 v[174:175], off
	v_mfma_f32_16x16x32_bf16 v[40:43], v[198:201], v[240:243], v[40:43]
	s_add_i32 m0, s20, 0x6000
	v_add_u32_e32 v252, v146, v144
	global_load_lds_dwordx4 v[156:157], off
	v_mfma_f32_16x16x32_bf16 v[36:39], v[202:205], v[240:243], v[36:39]
	s_add_i32 m0, s20, 0xe000
	v_mfma_f32_16x16x32_bf16 v[32:35], v[206:209], v[240:243], v[32:35]
	global_load_lds_dwordx4 v[158:159], off
	ds_read_b128 v[156:159], v155 offset:32768
	ds_read_b128 v[160:163], v155 offset:34816
	ds_read_b128 v[172:175], v155 offset:36864
	ds_read_b128 v[176:179], v155 offset:38912
	ds_read_b128 v[164:167], v252
	ds_read_b128 v[180:183], v252 offset:2048
	ds_read_b128 v[190:193], v252 offset:4096
	v_add_u32_e32 v155, v146, v150
	v_mfma_f32_16x16x32_bf16 v[28:31], v[194:197], v[244:247], v[28:31]
	v_mfma_f32_16x16x32_bf16 v[24:27], v[198:201], v[244:247], v[24:27]
	v_mfma_f32_16x16x32_bf16 v[20:23], v[202:205], v[244:247], v[20:23]
	v_mfma_f32_16x16x32_bf16 v[16:19], v[206:209], v[244:247], v[16:19]
	v_mfma_f32_16x16x32_bf16 v[12:15], v[194:197], v[248:251], v[12:15]
	v_mfma_f32_16x16x32_bf16 v[8:11], v[198:201], v[248:251], v[8:11]
	v_mfma_f32_16x16x32_bf16 v[4:7], v[202:205], v[248:251], v[4:7]
	v_mfma_f32_16x16x32_bf16 v[0:3], v[206:209], v[248:251], v[0:3]
	s_waitcnt lgkmcnt(2)
	v_mfma_f32_16x16x32_bf16 v[124:127], v[156:159], v[164:167], v[124:127]
	v_add_u32_e32 v146, v146, v152
	v_mfma_f32_16x16x32_bf16 v[120:123], v[160:163], v[164:167], v[120:123]
	v_mfma_f32_16x16x32_bf16 v[116:119], v[172:175], v[164:167], v[116:119]
	v_mfma_f32_16x16x32_bf16 v[112:115], v[176:179], v[164:167], v[112:115]
	ds_read_b128 v[164:167], v155
	v_add_u32_e32 v155, s19, v145
	v_add_u32_e32 v203, v155, v151
	s_waitcnt lgkmcnt(2)
	v_mfma_f32_16x16x32_bf16 v[108:111], v[156:159], v[180:183], v[108:111]
	v_add_u32_e32 v206, v155, v153
	v_mfma_f32_16x16x32_bf16 v[104:107], v[160:163], v[180:183], v[104:107]
	v_mfma_f32_16x16x32_bf16 v[100:103], v[172:175], v[180:183], v[100:103]
	v_mfma_f32_16x16x32_bf16 v[96:99], v[176:179], v[180:183], v[96:99]
	ds_read_b128 v[180:183], v252 offset:8192
	ds_read_b128 v[194:197], v203 offset:32768
	s_waitcnt lgkmcnt(3)
	v_mfma_f32_16x16x32_bf16 v[92:95], v[156:159], v[190:193], v[92:95]
	v_mfma_f32_16x16x32_bf16 v[88:91], v[160:163], v[190:193], v[88:91]
	v_mfma_f32_16x16x32_bf16 v[84:87], v[172:175], v[190:193], v[84:87]
	v_mfma_f32_16x16x32_bf16 v[80:83], v[176:179], v[190:193], v[80:83]
	ds_read_b128 v[190:193], v252 offset:10240
	ds_read_b128 v[198:201], v203 offset:34816
	s_waitcnt lgkmcnt(4)
	v_mfma_f32_16x16x32_bf16 v[76:79], v[156:159], v[164:167], v[76:79]
	v_mfma_f32_16x16x32_bf16 v[72:75], v[160:163], v[164:167], v[72:75]
	v_mfma_f32_16x16x32_bf16 v[68:71], v[172:175], v[164:167], v[68:71]
	v_mfma_f32_16x16x32_bf16 v[64:67], v[176:179], v[164:167], v[64:67]
	ds_read_b128 v[164:167], v252 offset:12288
	ds_read_b128 v[202:205], v203 offset:36864
	s_waitcnt lgkmcnt(5)
	v_mfma_f32_16x16x32_bf16 v[60:63], v[156:159], v[180:183], v[60:63]
	v_mfma_f32_16x16x32_bf16 v[56:59], v[160:163], v[180:183], v[56:59]
	v_mfma_f32_16x16x32_bf16 v[52:55], v[172:175], v[180:183], v[52:55]
	v_mfma_f32_16x16x32_bf16 v[48:51], v[176:179], v[180:183], v[48:51]
	ds_read_b128 v[206:209], v206 offset:38912
	ds_read_b128 v[180:183], v146
	v_add_u32_e32 v146, v155, v144
	s_waitcnt lgkmcnt(5)
	v_mfma_f32_16x16x32_bf16 v[44:47], v[156:159], v[190:193], v[44:47]
	v_mfma_f32_16x16x32_bf16 v[40:43], v[160:163], v[190:193], v[40:43]
	v_mfma_f32_16x16x32_bf16 v[36:39], v[172:175], v[190:193], v[36:39]
	v_mfma_f32_16x16x32_bf16 v[32:35], v[176:179], v[190:193], v[32:35]
	ds_read_b128 v[190:193], v146
	s_waitcnt lgkmcnt(4)
	v_mfma_f32_16x16x32_bf16 v[28:31], v[156:159], v[164:167], v[28:31]
	v_mfma_f32_16x16x32_bf16 v[24:27], v[160:163], v[164:167], v[24:27]
	v_mfma_f32_16x16x32_bf16 v[20:23], v[172:175], v[164:167], v[20:23]
	v_mfma_f32_16x16x32_bf16 v[16:19], v[176:179], v[164:167], v[16:19]
	ds_read_b128 v[164:167], v146 offset:2048
	s_waitcnt lgkmcnt(2)
; #define MFMA16(a, b, c) __builtin_amdgcn_mfma_f32_16x16x32_bf16((a), (b), (c), 0, 0, 0)
; DI bf16x8 ldfrag(const char* lds, int row, int chunk) { return *(const bf16x8*)(lds + swz(row, chunk)); }
; #define GEMM_SG1() do { __builtin_amdgcn_sched_group_barrier(0x100, 1, 0); __builtin_amdgcn_sched_group_barrier(0x008, 4, 0); } while (0)
; #define GEMM_SG2() do { __builtin_amdgcn_sched_group_barrier(0x100, 2, 0); __builtin_amdgcn_sched_group_barrier(0x008, 4, 0); } while (0)
; template <bool RSTD, bool SWAP>
; DI void gemm_tile(gacc_t& acc, const bf16_t* __restrict__ A, int lda, const bf16_t* __restrict__ Bt, int ldb, int K,
;                   char* lds, int tid, int wr, int wc, int lane, const float* ssq_row) {
;     ...
;     for (int kt = 0; kt < nk; ++kt) {
;         const char* cur = lds + (kt & 1) * 65536;
;         if (kt + 1 < nk) GEMM_ISSUE(kt + 1, (kt + 1) & 1);
;         bf16x8 bfr[2][4], afr[3];
; #pragma unroll
;         for (int n = 0; n < 4; ++n) bfr[0][n] = ldfrag(cur + 32768, wc * 64 + n * 16 + fr, fq);
;         afr[0] = ldfrag(cur, wr * 128 + fr, fq);
;         afr[1] = ldfrag(cur, wr * 128 + 16 + fr, fq);
; #pragma unroll
;         for (int idx = 0; idx < 16; ++idx) {
;             const int ks = idx >> 3, m = idx & 7;
;             if (idx < 14) afr[(idx + 2) % 3] = ldfrag(cur, wr * 128 + ((idx + 2) & 7) * 16 + fr, ((idx + 2) >> 3) * 4 + fq);
;             if (ks == 0 && m >= 2 && m < 6) bfr[1][m - 2] = ldfrag(cur + 32768, wc * 64 + (m - 2) * 16 + fr, 4 + fq);
; #pragma unroll
;             for (int n = 0; n < 4; ++n) acc[m][n] = SWAP ? MFMA16(bfr[ks][n], afr[idx % 3], acc[m][n]) : MFMA16(afr[idx % 3], bfr[ks][n], acc[m][n]);
;         }
;         __builtin_amdgcn_sched_group_barrier(0x100, 6, 0);
;     ...
;         GEMM_SG1(); GEMM_SG1(); GEMM_SG2(); GEMM_SG2(); GEMM_SG2(); GEMM_SG2(); GEMM_SG1(); GEMM_SG1();
;         GEMM_SG1(); GEMM_SG1(); GEMM_SG1(); GEMM_SG1(); GEMM_SG1(); GEMM_SG1();
;         __builtin_amdgcn_sched_group_barrier(0x008, 8, 0);
;         __builtin_amdgcn_sched_barrier(0);
;         asm volatile("s_waitcnt vmcnt(0)" ::: "memory");
;         __syncthreads();
;     }
	v_mfma_f32_16x16x32_bf16 v[8:11], v[160:163], v[180:183], v[8:11]
	v_add_u32_e32 v160, v155, v150
	v_mfma_f32_16x16x32_bf16 v[12:15], v[156:159], v[180:183], v[12:15]
	v_mfma_f32_16x16x32_bf16 v[4:7], v[172:175], v[180:183], v[4:7]
	v_mfma_f32_16x16x32_bf16 v[0:3], v[176:179], v[180:183], v[0:3]
	ds_read_b128 v[156:159], v146 offset:4096
	s_waitcnt lgkmcnt(2)
	v_mfma_f32_16x16x32_bf16 v[124:127], v[194:197], v[190:193], v[124:127]
	v_mfma_f32_16x16x32_bf16 v[120:123], v[198:201], v[190:193], v[120:123]
	v_mfma_f32_16x16x32_bf16 v[116:119], v[202:205], v[190:193], v[116:119]
	v_mfma_f32_16x16x32_bf16 v[112:115], v[206:209], v[190:193], v[112:115]
	ds_read_b128 v[160:163], v160
	s_waitcnt lgkmcnt(2)
	v_mfma_f32_16x16x32_bf16 v[108:111], v[194:197], v[164:167], v[108:111]
	v_mfma_f32_16x16x32_bf16 v[104:107], v[198:201], v[164:167], v[104:107]
	v_mfma_f32_16x16x32_bf16 v[100:103], v[202:205], v[164:167], v[100:103]
	v_mfma_f32_16x16x32_bf16 v[96:99], v[206:209], v[164:167], v[96:99]
	ds_read_b128 v[236:239], v146 offset:8192
	s_waitcnt lgkmcnt(2)
	v_mfma_f32_16x16x32_bf16 v[92:95], v[194:197], v[156:159], v[92:95]
	v_mfma_f32_16x16x32_bf16 v[88:91], v[198:201], v[156:159], v[88:91]
	v_mfma_f32_16x16x32_bf16 v[84:87], v[202:205], v[156:159], v[84:87]
	v_mfma_f32_16x16x32_bf16 v[80:83], v[206:209], v[156:159], v[80:83]
	ds_read_b128 v[240:243], v146 offset:10240
	ds_read_b128 v[244:247], v146 offset:12288
	v_add_u32_e32 v146, v155, v152
	ds_read_b128 v[248:251], v146
	s_waitcnt lgkmcnt(4)
	v_mfma_f32_16x16x32_bf16 v[76:79], v[194:197], v[160:163], v[76:79]
	v_mfma_f32_16x16x32_bf16 v[72:75], v[198:201], v[160:163], v[72:75]
	v_mfma_f32_16x16x32_bf16 v[68:71], v[202:205], v[160:163], v[68:71]
	v_mfma_f32_16x16x32_bf16 v[64:67], v[206:209], v[160:163], v[64:67]
	s_waitcnt lgkmcnt(0)
	s_waitcnt vmcnt(0)
	s_add_u32 s4, s4, 0x80
	s_addc_u32 s5, s5, 0
	s_add_i32 s17, s17, 0x10000
	s_cmpk_eq_i32 s4, 0x780
	s_waitcnt vmcnt(0)
	s_cbranch_scc0 .Lkhead_281
	s_barrier
	v_mfma_f32_16x16x32_bf16 v[60:63], v[194:197], v[236:239], v[60:63]
	v_mfma_f32_16x16x32_bf16 v[56:59], v[198:201], v[236:239], v[56:59]
	v_mfma_f32_16x16x32_bf16 v[52:55], v[202:205], v[236:239], v[52:55]
	v_mfma_f32_16x16x32_bf16 v[48:51], v[206:209], v[236:239], v[48:51]
	v_mfma_f32_16x16x32_bf16 v[44:47], v[194:197], v[240:243], v[44:47]
	v_mfma_f32_16x16x32_bf16 v[40:43], v[198:201], v[240:243], v[40:43]
	v_mfma_f32_16x16x32_bf16 v[36:39], v[202:205], v[240:243], v[36:39]
	v_mfma_f32_16x16x32_bf16 v[32:35], v[206:209], v[240:243], v[32:35]
	v_mfma_f32_16x16x32_bf16 v[28:31], v[194:197], v[244:247], v[28:31]
	v_mfma_f32_16x16x32_bf16 v[24:27], v[198:201], v[244:247], v[24:27]
	v_mfma_f32_16x16x32_bf16 v[20:23], v[202:205], v[244:247], v[20:23]
	v_mfma_f32_16x16x32_bf16 v[16:19], v[206:209], v[244:247], v[16:19]
	v_mfma_f32_16x16x32_bf16 v[12:15], v[194:197], v[248:251], v[12:15]
	v_mfma_f32_16x16x32_bf16 v[8:11], v[198:201], v[248:251], v[8:11]
	v_mfma_f32_16x16x32_bf16 v[4:7], v[202:205], v[248:251], v[4:7]
	v_mfma_f32_16x16x32_bf16 v[0:3], v[206:209], v[248:251], v[0:3]
	v_add_u32_e32 v146, s18, v142
	v_add3_u32 v155, v146, v148, v149
	ds_read_b128 v[136:139], v155 offset:32768
	ds_read_b128 v[156:159], v155 offset:34816
	ds_read_b128 v[164:167], v155 offset:36864
	ds_read_b128 v[172:175], v155 offset:38912
	v_add_u32_e32 v198, v146, v144
	ds_read_b128 v[160:163], v198
	ds_read_b128 v[176:179], v198 offset:2048
	v_add_u32_e32 v155, v146, v150
	ds_read_b128 v[180:183], v198 offset:4096
	s_waitcnt lgkmcnt(2)
	v_mfma_f32_16x16x32_bf16 v[124:127], v[136:139], v[160:163], v[124:127]
	v_add_u32_e32 v146, v146, v152
	s_lshl_b64 s[16:17], s[8:9], 8
	v_mfma_f32_16x16x32_bf16 v[120:123], v[156:159], v[160:163], v[120:123]
	v_mfma_f32_16x16x32_bf16 v[116:119], v[164:167], v[160:163], v[116:119]
	v_mfma_f32_16x16x32_bf16 v[112:115], v[172:175], v[160:163], v[112:115]
	ds_read_b128 v[160:163], v155
	v_add_u32_e32 v155, s18, v145
	v_add_u32_e32 v199, v155, v151
	s_waitcnt lgkmcnt(2)
	v_mfma_f32_16x16x32_bf16 v[108:111], v[136:139], v[176:179], v[108:111]
	v_mfma_f32_16x16x32_bf16 v[104:107], v[156:159], v[176:179], v[104:107]
	v_mfma_f32_16x16x32_bf16 v[100:103], v[164:167], v[176:179], v[100:103]
	v_mfma_f32_16x16x32_bf16 v[96:99], v[172:175], v[176:179], v[96:99]
	ds_read_b128 v[176:179], v198 offset:8192
	ds_read_b128 v[190:193], v199 offset:32768
	s_waitcnt lgkmcnt(3)
	v_mfma_f32_16x16x32_bf16 v[92:95], v[136:139], v[180:183], v[92:95]
	v_mfma_f32_16x16x32_bf16 v[88:91], v[156:159], v[180:183], v[88:91]
	v_mfma_f32_16x16x32_bf16 v[84:87], v[164:167], v[180:183], v[84:87]
	v_mfma_f32_16x16x32_bf16 v[80:83], v[172:175], v[180:183], v[80:83]
	ds_read_b128 v[180:183], v198 offset:10240
	ds_read_b128 v[194:197], v199 offset:34816
	s_waitcnt lgkmcnt(4)
	v_mfma_f32_16x16x32_bf16 v[76:79], v[136:139], v[160:163], v[76:79]
	v_mfma_f32_16x16x32_bf16 v[72:75], v[156:159], v[160:163], v[72:75]
	v_mfma_f32_16x16x32_bf16 v[68:71], v[164:167], v[160:163], v[68:71]
	v_mfma_f32_16x16x32_bf16 v[64:67], v[172:175], v[160:163], v[64:67]
	ds_read_b128 v[160:163], v198 offset:12288
	ds_read_b128 v[198:201], v199 offset:36864
	s_waitcnt lgkmcnt(5)
	v_mfma_f32_16x16x32_bf16 v[60:63], v[136:139], v[176:179], v[60:63]
	v_mfma_f32_16x16x32_bf16 v[56:59], v[156:159], v[176:179], v[56:59]
	v_mfma_f32_16x16x32_bf16 v[52:55], v[164:167], v[176:179], v[52:55]
	v_mfma_f32_16x16x32_bf16 v[48:51], v[172:175], v[176:179], v[48:51]
	ds_read_b128 v[176:179], v146
	v_add_u32_e32 v146, v155, v153
	ds_read_b128 v[202:205], v146 offset:38912
	v_add_u32_e32 v146, v155, v144
	s_waitcnt lgkmcnt(5)
; #define MFMA16(a, b, c) __builtin_amdgcn_mfma_f32_16x16x32_bf16((a), (b), (c), 0, 0, 0)
; DI unsigned pk2(float a, float b) { f32x2 v = {a, b}; bf16x2_t r = __builtin_convertvector(v, bf16x2_t); return __builtin_bit_cast(unsigned, r); }
; DI bf16x8 ldfrag(const char* lds, int row, int chunk) { return *(const bf16x8*)(lds + swz(row, chunk)); }
; #define GEMM_SG1() do { __builtin_amdgcn_sched_group_barrier(0x100, 1, 0); __builtin_amdgcn_sched_group_barrier(0x008, 4, 0); } while (0)
; #define GEMM_SG2() do { __builtin_amdgcn_sched_group_barrier(0x100, 2, 0); __builtin_amdgcn_sched_group_barrier(0x008, 4, 0); } while (0)
; template <bool RSTD, bool SWAP>
; DI void gemm_tile(gacc_t& acc, const bf16_t* __restrict__ A, int lda, const bf16_t* __restrict__ Bt, int ldb, int K,
;                   char* lds, int tid, int wr, int wc, int lane, const float* ssq_row) {
;     ...
;         for (int idx = 0; idx < 16; ++idx) {
;             const int ks = idx >> 3, m = idx & 7;
;             if (idx < 14) afr[(idx + 2) % 3] = ldfrag(cur, wr * 128 + ((idx + 2) & 7) * 16 + fr, ((idx + 2) >> 3) * 4 + fq);
;             if (ks == 0 && m >= 2 && m < 6) bfr[1][m - 2] = ldfrag(cur + 32768, wc * 64 + (m - 2) * 16 + fr, 4 + fq);
; #pragma unroll
;             for (int n = 0; n < 4; ++n) acc[m][n] = SWAP ? MFMA16(bfr[ks][n], afr[idx % 3], acc[m][n]) : MFMA16(afr[idx % 3], bfr[ks][n], acc[m][n]);
;         }
;         __builtin_amdgcn_sched_group_barrier(0x100, 6, 0);
;     ...
;         GEMM_SG1(); GEMM_SG1(); GEMM_SG2(); GEMM_SG2(); GEMM_SG2(); GEMM_SG2(); GEMM_SG1(); GEMM_SG1();
;         GEMM_SG1(); GEMM_SG1(); GEMM_SG1(); GEMM_SG1(); GEMM_SG1(); GEMM_SG1();
;         __builtin_amdgcn_sched_group_barrier(0x008, 8, 0);
;         __builtin_amdgcn_sched_barrier(0);
;         asm volatile("s_waitcnt vmcnt(0)" ::: "memory");
;         __syncthreads();
;     DI void operator()(gacc_t& acc, int pm, int pn, char* lds, int tid, int wr, int wc, int lane) const {
;     ...
;         char* lbase = lds + (wr * 128 + fr) * 528 + (wc * 64 + 4 * fq) * 2;
; #pragma unroll
;         for (int m = 0; m < 8; ++m)
; #pragma unroll
;             for (int n = 0; n < 4; ++n) { u32x2 w; w.x = pk2(acc[m][n][0], acc[m][n][1]); w.y = pk2(acc[m][n][2], acc[m][n][3]); *(u32x2*)(lbase + m * 16 * 528 + n * 32) = w; }
	v_mfma_f32_16x16x32_bf16 v[44:47], v[136:139], v[180:183], v[44:47]
	v_mfma_f32_16x16x32_bf16 v[40:43], v[156:159], v[180:183], v[40:43]
	v_mfma_f32_16x16x32_bf16 v[36:39], v[164:167], v[180:183], v[36:39]
	v_mfma_f32_16x16x32_bf16 v[32:35], v[172:175], v[180:183], v[32:35]
	ds_read_b128 v[180:183], v146
	s_waitcnt lgkmcnt(4)
	v_mfma_f32_16x16x32_bf16 v[28:31], v[136:139], v[160:163], v[28:31]
	v_mfma_f32_16x16x32_bf16 v[24:27], v[156:159], v[160:163], v[24:27]
	v_mfma_f32_16x16x32_bf16 v[20:23], v[164:167], v[160:163], v[20:23]
	v_mfma_f32_16x16x32_bf16 v[16:19], v[172:175], v[160:163], v[16:19]
	ds_read_b128 v[160:163], v146 offset:2048
	s_waitcnt lgkmcnt(3)
	v_mfma_f32_16x16x32_bf16 v[8:11], v[156:159], v[176:179], v[8:11]
	v_add_u32_e32 v156, v155, v150
	v_mfma_f32_16x16x32_bf16 v[12:15], v[136:139], v[176:179], v[12:15]
	v_mfma_f32_16x16x32_bf16 v[4:7], v[164:167], v[176:179], v[4:7]
	v_mfma_f32_16x16x32_bf16 v[0:3], v[172:175], v[176:179], v[0:3]
	ds_read_b128 v[136:139], v146 offset:4096
	s_waitcnt lgkmcnt(2)
	v_mfma_f32_16x16x32_bf16 v[124:127], v[190:193], v[180:183], v[124:127]
	v_mfma_f32_16x16x32_bf16 v[120:123], v[194:197], v[180:183], v[120:123]
	v_mfma_f32_16x16x32_bf16 v[116:119], v[198:201], v[180:183], v[116:119]
	v_mfma_f32_16x16x32_bf16 v[112:115], v[202:205], v[180:183], v[112:115]
	ds_read_b128 v[156:159], v156
	s_waitcnt lgkmcnt(2)
	v_mfma_f32_16x16x32_bf16 v[108:111], v[190:193], v[160:163], v[108:111]
	v_mfma_f32_16x16x32_bf16 v[104:107], v[194:197], v[160:163], v[104:107]
	v_mfma_f32_16x16x32_bf16 v[100:103], v[198:201], v[160:163], v[100:103]
	v_mfma_f32_16x16x32_bf16 v[96:99], v[202:205], v[160:163], v[96:99]
	ds_read_b128 v[160:163], v146 offset:8192
	s_waitcnt lgkmcnt(2)
	v_mfma_f32_16x16x32_bf16 v[92:95], v[190:193], v[136:139], v[92:95]
	v_mfma_f32_16x16x32_bf16 v[88:91], v[194:197], v[136:139], v[88:91]
	v_mfma_f32_16x16x32_bf16 v[84:87], v[198:201], v[136:139], v[84:87]
	v_mfma_f32_16x16x32_bf16 v[80:83], v[202:205], v[136:139], v[80:83]
	ds_read_b128 v[136:139], v146 offset:10240
	s_waitcnt lgkmcnt(2)
	v_mfma_f32_16x16x32_bf16 v[76:79], v[190:193], v[156:159], v[76:79]
	v_mfma_f32_16x16x32_bf16 v[72:75], v[194:197], v[156:159], v[72:75]
	v_mfma_f32_16x16x32_bf16 v[68:71], v[198:201], v[156:159], v[68:71]
	v_mfma_f32_16x16x32_bf16 v[64:67], v[202:205], v[156:159], v[64:67]
	ds_read_b128 v[156:159], v146 offset:12288
	v_add_u32_e32 v146, v155, v152
	s_waitcnt lgkmcnt(2)
	v_mfma_f32_16x16x32_bf16 v[60:63], v[190:193], v[160:163], v[60:63]
	v_mfma_f32_16x16x32_bf16 v[56:59], v[194:197], v[160:163], v[56:59]
	v_mfma_f32_16x16x32_bf16 v[52:55], v[198:201], v[160:163], v[52:55]
	v_mfma_f32_16x16x32_bf16 v[48:51], v[202:205], v[160:163], v[48:51]
	ds_read_b128 v[160:163], v146
	s_waitcnt lgkmcnt(2)
	v_mfma_f32_16x16x32_bf16 v[44:47], v[190:193], v[136:139], v[44:47]
	v_mfma_f32_16x16x32_bf16 v[40:43], v[194:197], v[136:139], v[40:43]
	v_mfma_f32_16x16x32_bf16 v[36:39], v[198:201], v[136:139], v[36:39]
	v_mfma_f32_16x16x32_bf16 v[32:35], v[202:205], v[136:139], v[32:35]
	s_waitcnt lgkmcnt(1)
	v_mfma_f32_16x16x32_bf16 v[24:27], v[194:197], v[156:159], v[24:27]
	v_mfma_f32_16x16x32_bf16 v[20:23], v[198:201], v[156:159], v[20:23]
	v_mfma_f32_16x16x32_bf16 v[16:19], v[202:205], v[156:159], v[16:19]
	s_waitcnt lgkmcnt(0)
	v_mfma_f32_16x16x32_bf16 v[12:15], v[190:193], v[160:163], v[12:15]
	v_mfma_f32_16x16x32_bf16 v[8:11], v[194:197], v[160:163], v[8:11]
	v_mfma_f32_16x16x32_bf16 v[4:7], v[198:201], v[160:163], v[4:7]
	v_mfma_f32_16x16x32_bf16 v[0:3], v[202:205], v[160:163], v[0:3]
	v_mfma_f32_16x16x32_bf16 v[28:31], v[190:193], v[156:159], v[28:31]
	v_mov_b32_e32 v136, v141
	v_mov_b32_e32 v137, v140
	s_waitcnt vmcnt(0)
	s_barrier
	v_cvt_pk_bf16_f32 v124, v124, v125
	v_and_or_b32 v138, v136, 15, v143
	v_ashrrev_i32_e32 v139, 1, v136
	v_mul_lo_u32 v138, v138, s3
	v_and_b32_e32 v139, -8, v139
	v_add3_u32 v138, v154, v138, v139
	v_cvt_pk_bf16_f32 v125, v126, v127
	v_cvt_pk_bf16_f32 v120, v120, v121
	v_cvt_pk_bf16_f32 v121, v122, v123
	v_cvt_pk_bf16_f32 v116, v116, v117
	v_cvt_pk_bf16_f32 v117, v118, v119
	v_cvt_pk_bf16_f32 v112, v112, v113
	v_cvt_pk_bf16_f32 v113, v114, v115
	v_cvt_pk_bf16_f32 v108, v108, v109
	v_cvt_pk_bf16_f32 v109, v110, v111
	v_cvt_pk_bf16_f32 v104, v104, v105
	v_cvt_pk_bf16_f32 v105, v106, v107
	v_add_u32_e32 v106, 0x2000, v138
	v_cvt_pk_bf16_f32 v100, v100, v101
	v_cvt_pk_bf16_f32 v101, v102, v103
	v_cvt_pk_bf16_f32 v96, v96, v97
	v_cvt_pk_bf16_f32 v97, v98, v99
	v_cvt_pk_bf16_f32 v92, v92, v93
	v_cvt_pk_bf16_f32 v93, v94, v95
	v_cvt_pk_bf16_f32 v88, v88, v89
	v_cvt_pk_bf16_f32 v89, v90, v91
	v_add_u32_e32 v90, 0x4000, v138
	v_cvt_pk_bf16_f32 v84, v84, v85
	v_cvt_pk_bf16_f32 v85, v86, v87
	v_cvt_pk_bf16_f32 v80, v80, v81
	v_cvt_pk_bf16_f32 v81, v82, v83
	v_cvt_pk_bf16_f32 v76, v76, v77
	v_cvt_pk_bf16_f32 v77, v78, v79
	v_cvt_pk_bf16_f32 v72, v72, v73
	v_cvt_pk_bf16_f32 v73, v74, v75
	v_add_u32_e32 v74, 0x6000, v138
	v_cvt_pk_bf16_f32 v68, v68, v69
	v_cvt_pk_bf16_f32 v69, v70, v71
	v_cvt_pk_bf16_f32 v64, v64, v65
	v_cvt_pk_bf16_f32 v65, v66, v67
	v_cvt_pk_bf16_f32 v60, v60, v61
	v_cvt_pk_bf16_f32 v61, v62, v63
	v_cvt_pk_bf16_f32 v56, v56, v57
	v_cvt_pk_bf16_f32 v57, v58, v59
	v_add_u32_e32 v58, 0x8000, v138
	v_cvt_pk_bf16_f32 v52, v52, v53
	v_cvt_pk_bf16_f32 v53, v54, v55
	v_cvt_pk_bf16_f32 v48, v48, v49
	v_cvt_pk_bf16_f32 v49, v50, v51
	v_cvt_pk_bf16_f32 v44, v44, v45
	v_cvt_pk_bf16_f32 v45, v46, v47
	v_cvt_pk_bf16_f32 v40, v40, v41
; DI unsigned pk2(float a, float b) { f32x2 v = {a, b}; bf16x2_t r = __builtin_convertvector(v, bf16x2_t); return __builtin_bit_cast(unsigned, r); }
; DI float bflo(unsigned w) { return __uint_as_float(w << 16); }
; DI float bfhi(unsigned w) { return __uint_as_float(w & 0xffff0000u); }
;     DI void operator()(gacc_t& acc, int pm, int pn, char* lds, int tid, int wr, int wc, int lane) const {
;     ...
;             for (int n = 0; n < 4; ++n) { u32x2 w; w.x = pk2(acc[m][n][0], acc[m][n][1]); w.y = pk2(acc[m][n][2], acc[m][n][3]); *(u32x2*)(lbase + m * 16 * 528 + n * 32) = w; }
;         __builtin_amdgcn_sched_barrier(0);
;         __syncthreads();
;         __builtin_amdgcn_sched_barrier(0);
;         const int g = lane >> 5, j32 = lane & 31;
; #pragma unroll
;         for (int ib = 0; ib < 4; ++ib) {
;             __builtin_amdgcn_sched_barrier(0);
;             u32x4 xv[4];
; #pragma unroll
;             for (int u = 0; u < 4; ++u) {
;                 const long row = (long)pm * 256 + (ib * 4 + u) * 16 + wid * 2 + g;
;                 xv[u] = *(const u32x4*)(xold + row * 1024 + pn * 256 + j32 * 8);
;             }
; #pragma unroll
;             for (int u = 0; u < 4; ++u) {
;                 const int rloc = (ib * 4 + u) * 16 + wid * 2 + g;
;                 const long row = (long)pm * 256 + rloc;
;                 const u32x4 a = *(const u32x4*)(lds + rloc * 528 + j32 * 16);
;                 u32x4 w; float ss = 0.f;
; #pragma unroll
;                 for (int e = 0; e < 4; ++e) {
;                     w[e] = pk2(bflo(xv[u][e]) + bflo(a[e]), bfhi(xv[u][e]) + bfhi(a[e]));
;                     const float b0 = bflo(w[e]), b1 = bfhi(w[e]);
;                     ss += b0 * b0 + b1 * b1;
;                 }
;                 *(u32x4*)(xnew + row * 1024 + pn * 256 + j32 * 8) = w;
; #pragma unroll
;                 for (int o = 1; o < 32; o <<= 1) ss += __shfl_xor(ss, o);
;                 if (j32 == 0) ssq[row * 4 + pn] = ss;
	v_cvt_pk_bf16_f32 v41, v42, v43
	v_add_u32_e32 v42, 0xa000, v138
	v_cvt_pk_bf16_f32 v36, v36, v37
	v_cvt_pk_bf16_f32 v37, v38, v39
	v_cvt_pk_bf16_f32 v32, v32, v33
	v_cvt_pk_bf16_f32 v33, v34, v35
	v_cvt_pk_bf16_f32 v28, v28, v29
	v_cvt_pk_bf16_f32 v29, v30, v31
	v_cvt_pk_bf16_f32 v24, v24, v25
	v_cvt_pk_bf16_f32 v25, v26, v27
	v_add_u32_e32 v26, 0xc000, v138
	v_cvt_pk_bf16_f32 v20, v20, v21
	v_cvt_pk_bf16_f32 v21, v22, v23
	v_cvt_pk_bf16_f32 v16, v16, v17
	v_cvt_pk_bf16_f32 v17, v18, v19
	v_cvt_pk_bf16_f32 v12, v12, v13
	v_cvt_pk_bf16_f32 v13, v14, v15
	v_cvt_pk_bf16_f32 v8, v8, v9
	v_cvt_pk_bf16_f32 v9, v10, v11
	v_add_u32_e32 v10, 0xe000, v138
	v_cvt_pk_bf16_f32 v4, v4, v5
	v_cvt_pk_bf16_f32 v5, v6, v7
	v_cvt_pk_bf16_f32 v0, v0, v1
	v_cvt_pk_bf16_f32 v1, v2, v3
	ds_write2_b64 v138, v[124:125], v[120:121] offset1:4
	ds_write2_b64 v138, v[116:117], v[112:113] offset0:8 offset1:12
	ds_write2_b64 v106, v[108:109], v[104:105] offset0:32 offset1:36
	ds_write2_b64 v106, v[100:101], v[96:97] offset0:40 offset1:44
	ds_write2_b64 v90, v[92:93], v[88:89] offset0:64 offset1:68
	ds_write2_b64 v90, v[84:85], v[80:81] offset0:72 offset1:76
	ds_write2_b64 v74, v[76:77], v[72:73] offset0:96 offset1:100
	ds_write2_b64 v74, v[68:69], v[64:65] offset0:104 offset1:108
	ds_write2_b64 v58, v[60:61], v[56:57] offset0:128 offset1:132
	ds_write2_b64 v58, v[52:53], v[48:49] offset0:136 offset1:140
	ds_write2_b64 v42, v[44:45], v[40:41] offset0:160 offset1:164
	ds_write2_b64 v42, v[36:37], v[32:33] offset0:168 offset1:172
	ds_write2_b64 v26, v[28:29], v[24:25] offset0:192 offset1:196
	ds_write2_b64 v26, v[20:21], v[16:17] offset0:200 offset1:204
	ds_write2_b64 v10, v[12:13], v[8:9] offset0:224 offset1:228
	ds_write2_b64 v10, v[4:5], v[0:1] offset0:232 offset1:236
	s_waitcnt lgkmcnt(0)
	s_barrier
	v_ashrrev_i32_e32 v0, 5, v136
	v_ashrrev_i32_e32 v1, 5, v137
	v_and_b32_e32 v23, 31, v136
	v_and_b32_e32 v2, -2, v1
	v_ashrrev_i32_e32 v1, 31, v0
	v_ashrrev_i32_e32 v3, 31, v2
	v_lshl_add_u64 v[4:5], s[16:17], 0, v[0:1]
	s_lshl_b32 s18, s6, 8
	v_lshlrev_b32_e32 v146, 4, v23
	v_lshl_add_u64 v[4:5], v[4:5], 0, v[2:3]
	s_ashr_i32 s19, s18, 31
	v_add_u32_e32 v16, v2, v0
	v_add_u32_e32 v22, 0, v146
	v_cmp_eq_u32_e64 s[4:5], 0, v23
	v_cmp_eq_u32_e64 s[98:99], 16, v23
	s_lshl_b64 s[20:21], s[18:19], 1
	s_add_u32 s30, s10, s20
	s_addc_u32 s31, s11, s21
	v_lshl_add_u64 v[0:1], s[30:31], 0, v[146:147]
	v_lshlrev_b64 v[2:3], 11, v[4:5]
	v_lshl_add_u64 v[18:19], v[0:1], 0, v[2:3]
	flat_load_dwordx4 v[12:15], v[18:19]
	v_add_co_u32_e32 v0, vcc, s49, v18
	v_mul_lo_u32 v24, v16, s3
	s_nop 0
	v_addc_co_u32_e32 v1, vcc, 0, v19, vcc
	flat_load_dwordx4 v[8:11], v[0:1]
	v_add_co_u32_e32 v0, vcc, s48, v18
	v_add_u32_e32 v20, v22, v24
	s_nop 0
	v_addc_co_u32_e32 v1, vcc, 0, v19, vcc
	flat_load_dwordx4 v[4:7], v[0:1]
	v_add_co_u32_e32 v0, vcc, s47, v18
	ds_read_b128 v[26:29], v20
	s_nop 0
	v_addc_co_u32_e32 v1, vcc, 0, v19, vcc
	flat_load_dwordx4 v[0:3], v[0:1]
	v_ashrrev_i32_e32 v17, 31, v16
	s_waitcnt lgkmcnt(0)
	v_lshlrev_b32_e32 v30, 16, v26
	v_and_b32_e32 v31, 0xffff0000, v26
	v_lshlrev_b32_e32 v26, 16, v27
	v_and_b32_e32 v27, 0xffff0000, v27
	s_waitcnt vmcnt(0)
	v_lshlrev_b32_e32 v20, 16, v12
	v_and_b32_e32 v21, 0xffff0000, v12
	v_pk_add_f32 v[20:21], v[20:21], v[30:31]
	s_nop 0
	v_cvt_pk_bf16_f32 v12, v20, v21
	v_and_b32_e32 v21, 0xffff0000, v12
	v_lshlrev_b32_e32 v20, 16, v12
	v_mul_f32_e32 v25, v21, v21
	v_fmac_f32_e32 v25, v20, v20
	v_lshlrev_b32_e32 v20, 16, v13
	v_and_b32_e32 v21, 0xffff0000, v13
	v_pk_add_f32 v[20:21], v[20:21], v[26:27]
	v_lshlrev_b32_e32 v26, 16, v28
	v_cvt_pk_bf16_f32 v13, v20, v21
	v_and_b32_e32 v21, 0xffff0000, v13
	v_lshlrev_b32_e32 v20, 16, v13
	v_mul_f32_e32 v21, v21, v21
	v_fmac_f32_e32 v21, v20, v20
	v_add_f32_e32 v25, v25, v21
	v_lshlrev_b32_e32 v20, 16, v14
	v_and_b32_e32 v21, 0xffff0000, v14
	v_and_b32_e32 v27, 0xffff0000, v28
	v_pk_add_f32 v[20:21], v[20:21], v[26:27]
	v_lshlrev_b32_e32 v26, 16, v29
	v_cvt_pk_bf16_f32 v14, v20, v21
	v_and_b32_e32 v21, 0xffff0000, v14
	v_lshlrev_b32_e32 v20, 16, v14
	v_mul_f32_e32 v21, v21, v21
	v_fmac_f32_e32 v21, v20, v20
	v_add_f32_e32 v25, v21, v25
	v_lshlrev_b32_e32 v20, 16, v15
	v_and_b32_e32 v21, 0xffff0000, v15
	v_and_b32_e32 v27, 0xffff0000, v29
	v_pk_add_f32 v[20:21], v[20:21], v[26:27]
	s_nop 0
	v_cvt_pk_bf16_f32 v15, v20, v21
	v_and_b32_e32 v21, 0xffff0000, v15
	v_lshlrev_b32_e32 v20, 16, v15
	v_mul_f32_e32 v21, v21, v21
	v_fmac_f32_e32 v21, v20, v20
	v_add_f32_e32 v25, v21, v25
	v_lshl_add_u64 v[20:21], s[16:17], 0, v[16:17]
	v_lshlrev_b64 v[26:27], 11, v[20:21]
	v_lshl_add_u64 v[26:27], s[68:69], 0, v[26:27]
	v_lshl_add_u64 v[26:27], v[26:27], 0, s[20:21]
	v_lshl_add_u64 v[26:27], v[26:27], 0, v[146:147]
	flat_store_dwordx4 v[26:27], v[12:15]
	s_nop 1
	v_add_f32_dpp v86, v25, v25 quad_perm:[1,0,3,2] row_mask:0xf bank_mask:0xf
	s_nop 1
	v_add_f32_dpp v86, v86, v86 quad_perm:[2,3,0,1] row_mask:0xf bank_mask:0xf
	s_nop 1
	v_add_f32_dpp v86, v86, v86 row_half_mirror row_mask:0xf bank_mask:0xf
	s_nop 1
	v_add_f32_dpp v86, v86, v86 row_mirror row_mask:0xf bank_mask:0xf
	s_nop 1
	v_add_f32_dpp v86, v86, v86 row_bcast:15 row_mask:0xa bank_mask:0xf
	s_waitcnt lgkmcnt(0)
	s_waitcnt lgkmcnt(0)
	s_waitcnt lgkmcnt(0)
	s_waitcnt lgkmcnt(0)
	s_and_saveexec_b64 s[20:21], s[98:99]
	s_cbranch_execz .LBB0_284
	v_lshl_add_u64 v[14:15], v[20:21], 4, s[78:79]
	v_lshl_add_u64 v[14:15], s[6:7], 2, v[14:15]
	s_waitcnt lgkmcnt(0)
	v_mov_b32_e32 v12, v86
	flat_store_dword v[14:15], v12

; #define MFMA16(a, b, c) __builtin_amdgcn_mfma_f32_16x16x32_bf16((a), (b), (c), 0, 0, 0)
; DI bf16x8 ldfrag(const char* lds, int row, int chunk) { return *(const bf16x8*)(lds + swz(row, chunk)); }
; template <bool RSTD, bool SWAP>
; DI void gemm_tile(gacc_t& acc, const bf16_t* __restrict__ A, int lda, const bf16_t* __restrict__ Bt, int ldb, int K,
;                   char* lds, int tid, int wr, int wc, int lane, const float* ssq_row) {
;     ...
;     GEMM_ISSUE(0, 0);
;     if (RSTD && tid < 256) {
;         const f32x4 q = *(const f32x4*)ssq_row;
;         ((float*)(lds + RSTD_OFF))[tid] = 1.0f / sqrtf(((q.x + q.y) + (q.z + q.w)) * (1.0f / 1024.0f) + 1e-6f);
;     }
;     asm volatile("s_waitcnt vmcnt(0)" ::: "memory");
;     __syncthreads();
;     for (int kt = 0; kt < nk; ++kt) {
;         const char* cur = lds + (kt & 1) * 65536;
;         if (kt + 1 < nk) GEMM_ISSUE(kt + 1, (kt + 1) & 1);
;         bf16x8 bfr[2][4], afr[3];
; #pragma unroll
;         for (int n = 0; n < 4; ++n) bfr[0][n] = ldfrag(cur + 32768, wc * 64 + n * 16 + fr, fq);
;         afr[0] = ldfrag(cur, wr * 128 + fr, fq);
;         afr[1] = ldfrag(cur, wr * 128 + 16 + fr, fq);
; #pragma unroll
;         for (int idx = 0; idx < 16; ++idx) {
;             const int ks = idx >> 3, m = idx & 7;
;             if (idx < 14) afr[(idx + 2) % 3] = ldfrag(cur, wr * 128 + ((idx + 2) & 7) * 16 + fr, ((idx + 2) >> 3) * 4 + fq);
;             if (ks == 0 && m >= 2 && m < 6) bfr[1][m - 2] = ldfrag(cur + 32768, wc * 64 + (m - 2) * 16 + fr, 4 + fq);
; #pragma unroll
;             for (int n = 0; n < 4; ++n) acc[m][n] = SWAP ? MFMA16(bfr[ks][n], afr[idx % 3], acc[m][n]) : MFMA16(afr[idx % 3], bfr[ks][n], acc[m][n]);
.LBB0_523:
	v_lshl_add_u64 v[158:159], v[136:137], 0, s[4:5]
	s_mov_b64 s[18:19], 0x800080
	v_lshl_add_u64 v[162:163], v[158:159], 0, s[18:19]
	s_mov_b64 s[18:19], 0x820080
	s_add_i32 s16, s13, 0xffff0000
	s_and_b32 s17, s13, 0x10000
	v_lshl_add_u64 v[166:167], v[158:159], 0, s[18:19]
	s_mov_b64 s[18:19], 0x840080
	s_and_b32 s21, s16, 0x10000
	s_add_i32 s16, s17, 0
	v_lshl_add_u64 v[174:175], v[158:159], 0, s[18:19]
	s_mov_b64 s[18:19], 0x860080
	v_lshl_add_u64 v[156:157], v[138:139], 0, s[4:5]
	v_lshl_add_u64 v[158:159], v[158:159], 0, s[18:19]
	s_add_i32 s18, s16, s12
	v_lshl_add_u64 v[160:161], v[156:157], 0, s[14:15]
	s_add_i32 s19, s18, 0x8000
	s_mov_b32 m0, s18
	v_lshl_add_u64 v[164:165], v[156:157], 0, s[72:73]
	global_load_lds_dwordx4 v[160:161], off
	v_mfma_f32_16x16x32_bf16 v[60:63], v[202:205], v[236:239], v[60:63]
	s_mov_b32 m0, s19
	v_lshl_add_u64 v[172:173], v[156:157], 0, s[76:77]
	global_load_lds_dwordx4 v[162:163], off
	v_mfma_f32_16x16x32_bf16 v[56:59], v[206:209], v[236:239], v[56:59]
	s_add_i32 m0, s18, 0x2000
	v_lshl_add_u64 v[156:157], v[156:157], 0, s[0:1]
	global_load_lds_dwordx4 v[164:165], off
	v_mfma_f32_16x16x32_bf16 v[52:55], v[210:213], v[236:239], v[52:55]
	s_add_i32 m0, s18, 0xa000
	s_add_i32 s17, s21, 0
	global_load_lds_dwordx4 v[166:167], off
	v_mfma_f32_16x16x32_bf16 v[48:51], v[214:217], v[236:239], v[48:51]
	s_add_i32 m0, s18, 0x4000
	v_add_u32_e32 v146, s17, v142
	global_load_lds_dwordx4 v[172:173], off
	v_mfma_f32_16x16x32_bf16 v[44:47], v[202:205], v[240:243], v[44:47]
	s_add_i32 m0, s18, 0xc000
	v_add3_u32 v155, v146, v148, v149
	global_load_lds_dwordx4 v[174:175], off
	v_mfma_f32_16x16x32_bf16 v[40:43], v[206:209], v[240:243], v[40:43]
	s_add_i32 m0, s18, 0x6000
	v_add_u32_e32 v176, v146, v144
	global_load_lds_dwordx4 v[156:157], off
	v_mfma_f32_16x16x32_bf16 v[36:39], v[210:213], v[240:243], v[36:39]
	s_add_i32 m0, s18, 0xe000
	v_mfma_f32_16x16x32_bf16 v[32:35], v[214:217], v[240:243], v[32:35]
	global_load_lds_dwordx4 v[158:159], off
	ds_read_b128 v[156:159], v155 offset:32768
	ds_read_b128 v[160:163], v155 offset:34816
	ds_read_b128 v[186:189], v155 offset:36864
	ds_read_b128 v[190:193], v155 offset:38912
	ds_read_b128 v[164:167], v176
	ds_read_b128 v[194:197], v176 offset:2048
	v_add_u32_e32 v155, v146, v150
	ds_read_b128 v[198:201], v176 offset:4096
	v_mfma_f32_16x16x32_bf16 v[28:31], v[202:205], v[244:247], v[28:31]
	v_mfma_f32_16x16x32_bf16 v[24:27], v[206:209], v[244:247], v[24:27]
	v_mfma_f32_16x16x32_bf16 v[20:23], v[210:213], v[244:247], v[20:23]
	v_mfma_f32_16x16x32_bf16 v[16:19], v[214:217], v[244:247], v[16:19]
	v_mfma_f32_16x16x32_bf16 v[12:15], v[202:205], v[248:251], v[12:15]
	v_mfma_f32_16x16x32_bf16 v[8:11], v[206:209], v[248:251], v[8:11]
	v_mfma_f32_16x16x32_bf16 v[4:7], v[210:213], v[248:251], v[4:7]
	v_mfma_f32_16x16x32_bf16 v[0:3], v[214:217], v[248:251], v[0:3]
	s_waitcnt lgkmcnt(2)
	v_mfma_f32_16x16x32_bf16 v[124:127], v[156:159], v[164:167], v[124:127]
	v_add_u32_e32 v146, v146, v152
	v_mfma_f32_16x16x32_bf16 v[120:123], v[160:163], v[164:167], v[120:123]
	v_mfma_f32_16x16x32_bf16 v[116:119], v[186:189], v[164:167], v[116:119]
	v_mfma_f32_16x16x32_bf16 v[112:115], v[190:193], v[164:167], v[112:115]
	ds_read_b128 v[164:167], v155
	v_add_u32_e32 v155, s17, v145
	v_add_u32_e32 v172, v155, v151
	s_waitcnt lgkmcnt(2)
	v_mfma_f32_16x16x32_bf16 v[108:111], v[156:159], v[194:197], v[108:111]
	v_mfma_f32_16x16x32_bf16 v[104:107], v[160:163], v[194:197], v[104:107]
	v_mfma_f32_16x16x32_bf16 v[100:103], v[186:189], v[194:197], v[100:103]
	v_mfma_f32_16x16x32_bf16 v[96:99], v[190:193], v[194:197], v[96:99]
	ds_read_b128 v[194:197], v176 offset:8192
	ds_read_b128 v[202:205], v172 offset:32768
	s_waitcnt lgkmcnt(3)
	v_mfma_f32_16x16x32_bf16 v[92:95], v[156:159], v[198:201], v[92:95]
	v_mfma_f32_16x16x32_bf16 v[88:91], v[160:163], v[198:201], v[88:91]
	v_mfma_f32_16x16x32_bf16 v[84:87], v[186:189], v[198:201], v[84:87]
	v_mfma_f32_16x16x32_bf16 v[80:83], v[190:193], v[198:201], v[80:83]
	ds_read_b128 v[198:201], v176 offset:10240
	ds_read_b128 v[206:209], v172 offset:34816
	s_waitcnt lgkmcnt(4)
	v_mfma_f32_16x16x32_bf16 v[76:79], v[156:159], v[164:167], v[76:79]
	v_mfma_f32_16x16x32_bf16 v[72:75], v[160:163], v[164:167], v[72:75]
	v_mfma_f32_16x16x32_bf16 v[68:71], v[186:189], v[164:167], v[68:71]
	v_mfma_f32_16x16x32_bf16 v[64:67], v[190:193], v[164:167], v[64:67]
	ds_read_b128 v[210:213], v172 offset:36864
	v_add_u32_e32 v172, v155, v153
	ds_read_b128 v[164:167], v176 offset:12288
	s_waitcnt lgkmcnt(5)
	v_mfma_f32_16x16x32_bf16 v[60:63], v[156:159], v[194:197], v[60:63]
	v_mfma_f32_16x16x32_bf16 v[56:59], v[160:163], v[194:197], v[56:59]
	v_mfma_f32_16x16x32_bf16 v[52:55], v[186:189], v[194:197], v[52:55]
	v_mfma_f32_16x16x32_bf16 v[48:51], v[190:193], v[194:197], v[48:51]
	ds_read_b128 v[214:217], v172 offset:38912
	ds_read_b128 v[194:197], v146
	v_add_u32_e32 v146, v155, v144
	s_waitcnt lgkmcnt(5)
	v_mfma_f32_16x16x32_bf16 v[44:47], v[156:159], v[198:201], v[44:47]
	v_mfma_f32_16x16x32_bf16 v[40:43], v[160:163], v[198:201], v[40:43]
	v_mfma_f32_16x16x32_bf16 v[36:39], v[186:189], v[198:201], v[36:39]
	v_mfma_f32_16x16x32_bf16 v[32:35], v[190:193], v[198:201], v[32:35]
	ds_read_b128 v[198:201], v146
	s_waitcnt lgkmcnt(3)
	v_mfma_f32_16x16x32_bf16 v[28:31], v[156:159], v[164:167], v[28:31]
	v_mfma_f32_16x16x32_bf16 v[24:27], v[160:163], v[164:167], v[24:27]
	v_mfma_f32_16x16x32_bf16 v[20:23], v[186:189], v[164:167], v[20:23]
	v_mfma_f32_16x16x32_bf16 v[16:19], v[190:193], v[164:167], v[16:19]
	ds_read_b128 v[164:167], v146 offset:2048
	s_waitcnt lgkmcnt(2)
; #define MFMA16(a, b, c) __builtin_amdgcn_mfma_f32_16x16x32_bf16((a), (b), (c), 0, 0, 0)
; DI bf16x8 ldfrag(const char* lds, int row, int chunk) { return *(const bf16x8*)(lds + swz(row, chunk)); }
; #define GEMM_SG1() do { __builtin_amdgcn_sched_group_barrier(0x100, 1, 0); __builtin_amdgcn_sched_group_barrier(0x008, 4, 0); } while (0)
; #define GEMM_SG2() do { __builtin_amdgcn_sched_group_barrier(0x100, 2, 0); __builtin_amdgcn_sched_group_barrier(0x008, 4, 0); } while (0)
; template <bool RSTD, bool SWAP>
; DI void gemm_tile(gacc_t& acc, const bf16_t* __restrict__ A, int lda, const bf16_t* __restrict__ Bt, int ldb, int K,
;                   char* lds, int tid, int wr, int wc, int lane, const float* ssq_row) {
;     ...
;     for (int kt = 0; kt < nk; ++kt) {
;         const char* cur = lds + (kt & 1) * 65536;
;         if (kt + 1 < nk) GEMM_ISSUE(kt + 1, (kt + 1) & 1);
;         bf16x8 bfr[2][4], afr[3];
; #pragma unroll
;         for (int n = 0; n < 4; ++n) bfr[0][n] = ldfrag(cur + 32768, wc * 64 + n * 16 + fr, fq);
;         afr[0] = ldfrag(cur, wr * 128 + fr, fq);
;         afr[1] = ldfrag(cur, wr * 128 + 16 + fr, fq);
; #pragma unroll
;         for (int idx = 0; idx < 16; ++idx) {
;             const int ks = idx >> 3, m = idx & 7;
;             if (idx < 14) afr[(idx + 2) % 3] = ldfrag(cur, wr * 128 + ((idx + 2) & 7) * 16 + fr, ((idx + 2) >> 3) * 4 + fq);
;             if (ks == 0 && m >= 2 && m < 6) bfr[1][m - 2] = ldfrag(cur + 32768, wc * 64 + (m - 2) * 16 + fr, 4 + fq);
; #pragma unroll
;             for (int n = 0; n < 4; ++n) acc[m][n] = SWAP ? MFMA16(bfr[ks][n], afr[idx % 3], acc[m][n]) : MFMA16(afr[idx % 3], bfr[ks][n], acc[m][n]);
;         }
;         __builtin_amdgcn_sched_group_barrier(0x100, 6, 0);
;     ...
;         GEMM_SG1(); GEMM_SG1(); GEMM_SG2(); GEMM_SG2(); GEMM_SG2(); GEMM_SG2(); GEMM_SG1(); GEMM_SG1();
;         GEMM_SG1(); GEMM_SG1(); GEMM_SG1(); GEMM_SG1(); GEMM_SG1(); GEMM_SG1();
;         __builtin_amdgcn_sched_group_barrier(0x008, 8, 0);
;         __builtin_amdgcn_sched_barrier(0);
;         asm volatile("s_waitcnt vmcnt(0)" ::: "memory");
;         __syncthreads();
;     }
	v_mfma_f32_16x16x32_bf16 v[8:11], v[160:163], v[194:197], v[8:11]
	v_add_u32_e32 v160, v155, v150
	v_mfma_f32_16x16x32_bf16 v[12:15], v[156:159], v[194:197], v[12:15]
	v_mfma_f32_16x16x32_bf16 v[4:7], v[186:189], v[194:197], v[4:7]
	v_mfma_f32_16x16x32_bf16 v[0:3], v[190:193], v[194:197], v[0:3]
	ds_read_b128 v[156:159], v146 offset:4096
	s_waitcnt lgkmcnt(2)
	v_mfma_f32_16x16x32_bf16 v[124:127], v[202:205], v[198:201], v[124:127]
	v_mfma_f32_16x16x32_bf16 v[120:123], v[206:209], v[198:201], v[120:123]
	v_mfma_f32_16x16x32_bf16 v[116:119], v[210:213], v[198:201], v[116:119]
	v_mfma_f32_16x16x32_bf16 v[112:115], v[214:217], v[198:201], v[112:115]
	ds_read_b128 v[160:163], v160
	s_waitcnt lgkmcnt(2)
	v_mfma_f32_16x16x32_bf16 v[108:111], v[202:205], v[164:167], v[108:111]
	v_mfma_f32_16x16x32_bf16 v[104:107], v[206:209], v[164:167], v[104:107]
	v_mfma_f32_16x16x32_bf16 v[100:103], v[210:213], v[164:167], v[100:103]
	v_mfma_f32_16x16x32_bf16 v[96:99], v[214:217], v[164:167], v[96:99]
	ds_read_b128 v[236:239], v146 offset:8192
	s_waitcnt lgkmcnt(2)
	v_mfma_f32_16x16x32_bf16 v[92:95], v[202:205], v[156:159], v[92:95]
	v_mfma_f32_16x16x32_bf16 v[88:91], v[206:209], v[156:159], v[88:91]
	v_mfma_f32_16x16x32_bf16 v[84:87], v[210:213], v[156:159], v[84:87]
	v_mfma_f32_16x16x32_bf16 v[80:83], v[214:217], v[156:159], v[80:83]
	ds_read_b128 v[240:243], v146 offset:10240
	ds_read_b128 v[244:247], v146 offset:12288
	v_add_u32_e32 v146, v155, v152
	ds_read_b128 v[248:251], v146
	s_waitcnt lgkmcnt(4)
	v_mfma_f32_16x16x32_bf16 v[76:79], v[202:205], v[160:163], v[76:79]
	v_mfma_f32_16x16x32_bf16 v[72:75], v[206:209], v[160:163], v[72:75]
	v_mfma_f32_16x16x32_bf16 v[68:71], v[210:213], v[160:163], v[68:71]
	v_mfma_f32_16x16x32_bf16 v[64:67], v[214:217], v[160:163], v[64:67]
	s_waitcnt lgkmcnt(0)
	s_waitcnt vmcnt(0)
	s_add_u32 s4, s4, 0x80
	s_addc_u32 s5, s5, 0
	s_add_i32 s13, s13, 0x10000
	s_cmpk_eq_i32 s4, 0x780
	s_waitcnt vmcnt(0)
	s_cbranch_scc0 .Lkhead_523
	s_barrier
	v_mfma_f32_16x16x32_bf16 v[60:63], v[202:205], v[236:239], v[60:63]
	v_mfma_f32_16x16x32_bf16 v[56:59], v[206:209], v[236:239], v[56:59]
	v_mfma_f32_16x16x32_bf16 v[52:55], v[210:213], v[236:239], v[52:55]
	v_mfma_f32_16x16x32_bf16 v[48:51], v[214:217], v[236:239], v[48:51]
	v_mfma_f32_16x16x32_bf16 v[44:47], v[202:205], v[240:243], v[44:47]
	v_mfma_f32_16x16x32_bf16 v[40:43], v[206:209], v[240:243], v[40:43]
	v_mfma_f32_16x16x32_bf16 v[36:39], v[210:213], v[240:243], v[36:39]
	v_mfma_f32_16x16x32_bf16 v[32:35], v[214:217], v[240:243], v[32:35]
	v_mfma_f32_16x16x32_bf16 v[28:31], v[202:205], v[244:247], v[28:31]
	v_mfma_f32_16x16x32_bf16 v[24:27], v[206:209], v[244:247], v[24:27]
	v_mfma_f32_16x16x32_bf16 v[20:23], v[210:213], v[244:247], v[20:23]
	v_mfma_f32_16x16x32_bf16 v[16:19], v[214:217], v[244:247], v[16:19]
	v_mfma_f32_16x16x32_bf16 v[12:15], v[202:205], v[248:251], v[12:15]
	v_mfma_f32_16x16x32_bf16 v[8:11], v[206:209], v[248:251], v[8:11]
	v_mfma_f32_16x16x32_bf16 v[4:7], v[210:213], v[248:251], v[4:7]
	v_mfma_f32_16x16x32_bf16 v[0:3], v[214:217], v[248:251], v[0:3]
	v_add_u32_e32 v146, s16, v142
	v_add3_u32 v155, v146, v148, v149
	ds_read_b128 v[136:139], v155 offset:32768
	ds_read_b128 v[156:159], v155 offset:34816
	ds_read_b128 v[164:167], v155 offset:36864
	ds_read_b128 v[186:189], v155 offset:38912
	v_add_u32_e32 v172, v146, v144
	ds_read_b128 v[160:163], v172
	ds_read_b128 v[190:193], v172 offset:2048
	v_add_u32_e32 v155, v146, v150
	ds_read_b128 v[194:197], v172 offset:4096
	s_waitcnt lgkmcnt(2)
	v_mfma_f32_16x16x32_bf16 v[124:127], v[136:139], v[160:163], v[124:127]
	v_add_u32_e32 v146, v146, v152
	s_lshl_b64 s[12:13], s[8:9], 8
	v_mfma_f32_16x16x32_bf16 v[120:123], v[156:159], v[160:163], v[120:123]
	v_mfma_f32_16x16x32_bf16 v[116:119], v[164:167], v[160:163], v[116:119]
	v_mfma_f32_16x16x32_bf16 v[112:115], v[186:189], v[160:163], v[112:115]
	ds_read_b128 v[160:163], v155
	v_add_u32_e32 v155, s16, v145
	v_add_u32_e32 v173, v155, v151
	s_waitcnt lgkmcnt(2)
	v_mfma_f32_16x16x32_bf16 v[108:111], v[136:139], v[190:193], v[108:111]
	v_mfma_f32_16x16x32_bf16 v[104:107], v[156:159], v[190:193], v[104:107]
	v_mfma_f32_16x16x32_bf16 v[100:103], v[164:167], v[190:193], v[100:103]
	v_mfma_f32_16x16x32_bf16 v[96:99], v[186:189], v[190:193], v[96:99]
	ds_read_b128 v[190:193], v172 offset:8192
	ds_read_b128 v[198:201], v173 offset:32768
	s_waitcnt lgkmcnt(3)
	v_mfma_f32_16x16x32_bf16 v[92:95], v[136:139], v[194:197], v[92:95]
	v_mfma_f32_16x16x32_bf16 v[88:91], v[156:159], v[194:197], v[88:91]
	v_mfma_f32_16x16x32_bf16 v[84:87], v[164:167], v[194:197], v[84:87]
	v_mfma_f32_16x16x32_bf16 v[80:83], v[186:189], v[194:197], v[80:83]
	ds_read_b128 v[194:197], v172 offset:10240
	ds_read_b128 v[202:205], v173 offset:34816
	s_waitcnt lgkmcnt(4)
	v_mfma_f32_16x16x32_bf16 v[76:79], v[136:139], v[160:163], v[76:79]
	v_mfma_f32_16x16x32_bf16 v[72:75], v[156:159], v[160:163], v[72:75]
	v_mfma_f32_16x16x32_bf16 v[68:71], v[164:167], v[160:163], v[68:71]
	v_mfma_f32_16x16x32_bf16 v[64:67], v[186:189], v[160:163], v[64:67]
	ds_read_b128 v[160:163], v172 offset:12288
	ds_read_b128 v[206:209], v173 offset:36864
	s_waitcnt lgkmcnt(5)
	v_mfma_f32_16x16x32_bf16 v[60:63], v[136:139], v[190:193], v[60:63]
	v_mfma_f32_16x16x32_bf16 v[56:59], v[156:159], v[190:193], v[56:59]
	v_mfma_f32_16x16x32_bf16 v[52:55], v[164:167], v[190:193], v[52:55]
	v_mfma_f32_16x16x32_bf16 v[48:51], v[186:189], v[190:193], v[48:51]
	ds_read_b128 v[190:193], v146
	v_add_u32_e32 v146, v155, v153
	ds_read_b128 v[210:213], v146 offset:38912
	v_add_u32_e32 v146, v155, v144
	s_waitcnt lgkmcnt(5)
; #define MFMA16(a, b, c) __builtin_amdgcn_mfma_f32_16x16x32_bf16((a), (b), (c), 0, 0, 0)
; DI unsigned pk2(float a, float b) { f32x2 v = {a, b}; bf16x2_t r = __builtin_convertvector(v, bf16x2_t); return __builtin_bit_cast(unsigned, r); }
; DI bf16x8 ldfrag(const char* lds, int row, int chunk) { return *(const bf16x8*)(lds + swz(row, chunk)); }
; template <bool RSTD, bool SWAP>
; DI void gemm_tile(gacc_t& acc, const bf16_t* __restrict__ A, int lda, const bf16_t* __restrict__ Bt, int ldb, int K,
;                   char* lds, int tid, int wr, int wc, int lane, const float* ssq_row) {
;     ...
;         for (int idx = 0; idx < 16; ++idx) {
;             const int ks = idx >> 3, m = idx & 7;
;             if (idx < 14) afr[(idx + 2) % 3] = ldfrag(cur, wr * 128 + ((idx + 2) & 7) * 16 + fr, ((idx + 2) >> 3) * 4 + fq);
;             if (ks == 0 && m >= 2 && m < 6) bfr[1][m - 2] = ldfrag(cur + 32768, wc * 64 + (m - 2) * 16 + fr, 4 + fq);
; #pragma unroll
;             for (int n = 0; n < 4; ++n) acc[m][n] = SWAP ? MFMA16(bfr[ks][n], afr[idx % 3], acc[m][n]) : MFMA16(afr[idx % 3], bfr[ks][n], acc[m][n]);
;     DI void operator()(gacc_t& acc, int pm, int pn, char* lds, int tid, int wr, int wc, int lane) const {
;     ...
;         char* lbase = lds + (wr * 128 + fr) * 528 + (wc * 64 + 4 * fq) * 2;
; #pragma unroll
;         for (int m = 0; m < 8; ++m)
; #pragma unroll
;             for (int n = 0; n < 4; ++n) { u32x2 w; w.x = pk2(acc[m][n][0], acc[m][n][1]); w.y = pk2(acc[m][n][2], acc[m][n][3]); *(u32x2*)(lbase + m * 16 * 528 + n * 32) = w; }
	v_mfma_f32_16x16x32_bf16 v[44:47], v[136:139], v[194:197], v[44:47]
	v_mfma_f32_16x16x32_bf16 v[40:43], v[156:159], v[194:197], v[40:43]
	v_mfma_f32_16x16x32_bf16 v[36:39], v[164:167], v[194:197], v[36:39]
	v_mfma_f32_16x16x32_bf16 v[32:35], v[186:189], v[194:197], v[32:35]
	ds_read_b128 v[194:197], v146
	s_waitcnt lgkmcnt(4)
	v_mfma_f32_16x16x32_bf16 v[28:31], v[136:139], v[160:163], v[28:31]
	v_mfma_f32_16x16x32_bf16 v[24:27], v[156:159], v[160:163], v[24:27]
	v_mfma_f32_16x16x32_bf16 v[20:23], v[164:167], v[160:163], v[20:23]
	v_mfma_f32_16x16x32_bf16 v[16:19], v[186:189], v[160:163], v[16:19]
	ds_read_b128 v[160:163], v146 offset:2048
	s_waitcnt lgkmcnt(3)
	v_mfma_f32_16x16x32_bf16 v[8:11], v[156:159], v[190:193], v[8:11]
	v_add_u32_e32 v156, v155, v150
	v_mfma_f32_16x16x32_bf16 v[12:15], v[136:139], v[190:193], v[12:15]
	v_mfma_f32_16x16x32_bf16 v[4:7], v[164:167], v[190:193], v[4:7]
	v_mfma_f32_16x16x32_bf16 v[0:3], v[186:189], v[190:193], v[0:3]
	ds_read_b128 v[136:139], v146 offset:4096
	s_waitcnt lgkmcnt(2)
	v_mfma_f32_16x16x32_bf16 v[124:127], v[198:201], v[194:197], v[124:127]
	v_mfma_f32_16x16x32_bf16 v[120:123], v[202:205], v[194:197], v[120:123]
	v_mfma_f32_16x16x32_bf16 v[116:119], v[206:209], v[194:197], v[116:119]
	v_mfma_f32_16x16x32_bf16 v[112:115], v[210:213], v[194:197], v[112:115]
	ds_read_b128 v[156:159], v156
	s_waitcnt lgkmcnt(2)
	v_mfma_f32_16x16x32_bf16 v[108:111], v[198:201], v[160:163], v[108:111]
	v_mfma_f32_16x16x32_bf16 v[104:107], v[202:205], v[160:163], v[104:107]
	v_mfma_f32_16x16x32_bf16 v[100:103], v[206:209], v[160:163], v[100:103]
	v_mfma_f32_16x16x32_bf16 v[96:99], v[210:213], v[160:163], v[96:99]
	ds_read_b128 v[160:163], v146 offset:8192
	s_waitcnt lgkmcnt(2)
	v_mfma_f32_16x16x32_bf16 v[92:95], v[198:201], v[136:139], v[92:95]
	v_mfma_f32_16x16x32_bf16 v[88:91], v[202:205], v[136:139], v[88:91]
	v_mfma_f32_16x16x32_bf16 v[84:87], v[206:209], v[136:139], v[84:87]
	v_mfma_f32_16x16x32_bf16 v[80:83], v[210:213], v[136:139], v[80:83]
	ds_read_b128 v[136:139], v146 offset:10240
	s_waitcnt lgkmcnt(2)
	v_mfma_f32_16x16x32_bf16 v[76:79], v[198:201], v[156:159], v[76:79]
	v_mfma_f32_16x16x32_bf16 v[72:75], v[202:205], v[156:159], v[72:75]
	v_mfma_f32_16x16x32_bf16 v[68:71], v[206:209], v[156:159], v[68:71]
	v_mfma_f32_16x16x32_bf16 v[64:67], v[210:213], v[156:159], v[64:67]
	ds_read_b128 v[156:159], v146 offset:12288
	v_add_u32_e32 v146, v155, v152
	s_waitcnt lgkmcnt(2)
	v_mfma_f32_16x16x32_bf16 v[60:63], v[198:201], v[160:163], v[60:63]
	v_mfma_f32_16x16x32_bf16 v[56:59], v[202:205], v[160:163], v[56:59]
	v_mfma_f32_16x16x32_bf16 v[52:55], v[206:209], v[160:163], v[52:55]
	v_mfma_f32_16x16x32_bf16 v[48:51], v[210:213], v[160:163], v[48:51]
	ds_read_b128 v[160:163], v146
	s_waitcnt lgkmcnt(2)
	v_mfma_f32_16x16x32_bf16 v[44:47], v[198:201], v[136:139], v[44:47]
	v_mfma_f32_16x16x32_bf16 v[40:43], v[202:205], v[136:139], v[40:43]
	v_mfma_f32_16x16x32_bf16 v[36:39], v[206:209], v[136:139], v[36:39]
	v_mfma_f32_16x16x32_bf16 v[32:35], v[210:213], v[136:139], v[32:35]
	s_waitcnt lgkmcnt(1)
	v_mfma_f32_16x16x32_bf16 v[24:27], v[202:205], v[156:159], v[24:27]
	v_mfma_f32_16x16x32_bf16 v[20:23], v[206:209], v[156:159], v[20:23]
	v_mfma_f32_16x16x32_bf16 v[16:19], v[210:213], v[156:159], v[16:19]
	s_waitcnt lgkmcnt(0)
	v_mfma_f32_16x16x32_bf16 v[12:15], v[198:201], v[160:163], v[12:15]
	v_mfma_f32_16x16x32_bf16 v[8:11], v[202:205], v[160:163], v[8:11]
	v_mfma_f32_16x16x32_bf16 v[4:7], v[206:209], v[160:163], v[4:7]
	v_mfma_f32_16x16x32_bf16 v[0:3], v[210:213], v[160:163], v[0:3]
	v_mfma_f32_16x16x32_bf16 v[28:31], v[198:201], v[156:159], v[28:31]
	v_mov_b32_e32 v136, v141
	v_mov_b32_e32 v137, v140
	s_waitcnt vmcnt(0)
	s_barrier
	v_cvt_pk_bf16_f32 v124, v124, v125
	v_and_or_b32 v138, v136, 15, v143
	v_ashrrev_i32_e32 v139, 1, v136
	v_mul_lo_u32 v138, v138, s3
	v_and_b32_e32 v139, -8, v139
	v_add3_u32 v138, v154, v138, v139
	v_cvt_pk_bf16_f32 v125, v126, v127
	v_cvt_pk_bf16_f32 v120, v120, v121
	v_cvt_pk_bf16_f32 v121, v122, v123
	v_cvt_pk_bf16_f32 v116, v116, v117
	v_cvt_pk_bf16_f32 v117, v118, v119
	v_cvt_pk_bf16_f32 v112, v112, v113
	v_cvt_pk_bf16_f32 v113, v114, v115
	v_cvt_pk_bf16_f32 v108, v108, v109
	v_cvt_pk_bf16_f32 v109, v110, v111
	v_cvt_pk_bf16_f32 v104, v104, v105
	v_cvt_pk_bf16_f32 v105, v106, v107
	v_add_u32_e32 v106, 0x2000, v138
	v_cvt_pk_bf16_f32 v100, v100, v101
	v_cvt_pk_bf16_f32 v101, v102, v103
	v_cvt_pk_bf16_f32 v96, v96, v97
	v_cvt_pk_bf16_f32 v97, v98, v99
	v_cvt_pk_bf16_f32 v92, v92, v93
	v_cvt_pk_bf16_f32 v93, v94, v95
	v_cvt_pk_bf16_f32 v88, v88, v89
	v_cvt_pk_bf16_f32 v89, v90, v91
	v_add_u32_e32 v90, 0x4000, v138
	v_cvt_pk_bf16_f32 v84, v84, v85
	v_cvt_pk_bf16_f32 v85, v86, v87
	v_cvt_pk_bf16_f32 v80, v80, v81
	v_cvt_pk_bf16_f32 v81, v82, v83
	v_cvt_pk_bf16_f32 v76, v76, v77
	v_cvt_pk_bf16_f32 v77, v78, v79
	v_cvt_pk_bf16_f32 v72, v72, v73
	v_cvt_pk_bf16_f32 v73, v74, v75
	v_add_u32_e32 v74, 0x6000, v138
	v_cvt_pk_bf16_f32 v68, v68, v69
	v_cvt_pk_bf16_f32 v69, v70, v71
	v_cvt_pk_bf16_f32 v64, v64, v65
	v_cvt_pk_bf16_f32 v65, v66, v67
	v_cvt_pk_bf16_f32 v60, v60, v61
	v_cvt_pk_bf16_f32 v61, v62, v63
	v_cvt_pk_bf16_f32 v56, v56, v57
	v_cvt_pk_bf16_f32 v57, v58, v59
	v_add_u32_e32 v58, 0x8000, v138
	v_cvt_pk_bf16_f32 v52, v52, v53
	v_cvt_pk_bf16_f32 v53, v54, v55
	v_cvt_pk_bf16_f32 v48, v48, v49
	v_cvt_pk_bf16_f32 v49, v50, v51
	v_cvt_pk_bf16_f32 v44, v44, v45
	v_cvt_pk_bf16_f32 v45, v46, v47
	v_cvt_pk_bf16_f32 v40, v40, v41
	v_cvt_pk_bf16_f32 v41, v42, v43
	v_add_u32_e32 v42, 0xa000, v138
	v_cvt_pk_bf16_f32 v36, v36, v37
	v_cvt_pk_bf16_f32 v37, v38, v39
	v_cvt_pk_bf16_f32 v32, v32, v33
; DI unsigned pk2(float a, float b) { f32x2 v = {a, b}; bf16x2_t r = __builtin_convertvector(v, bf16x2_t); return __builtin_bit_cast(unsigned, r); }
; DI float bflo(unsigned w) { return __uint_as_float(w << 16); }
; DI float bfhi(unsigned w) { return __uint_as_float(w & 0xffff0000u); }
;     DI void operator()(gacc_t& acc, int pm, int pn, char* lds, int tid, int wr, int wc, int lane) const {
;     ...
;             for (int n = 0; n < 4; ++n) { u32x2 w; w.x = pk2(acc[m][n][0], acc[m][n][1]); w.y = pk2(acc[m][n][2], acc[m][n][3]); *(u32x2*)(lbase + m * 16 * 528 + n * 32) = w; }
;         __builtin_amdgcn_sched_barrier(0);
;         __syncthreads();
;         __builtin_amdgcn_sched_barrier(0);
;         const int g = lane >> 5, j32 = lane & 31;
; #pragma unroll
;         for (int ib = 0; ib < 4; ++ib) {
;             __builtin_amdgcn_sched_barrier(0);
;             u32x4 xv[4];
; #pragma unroll
;             for (int u = 0; u < 4; ++u) {
;                 const long row = (long)pm * 256 + (ib * 4 + u) * 16 + wid * 2 + g;
;                 xv[u] = *(const u32x4*)(xold + row * 1024 + pn * 256 + j32 * 8);
;             }
; #pragma unroll
;             for (int u = 0; u < 4; ++u) {
;                 const int rloc = (ib * 4 + u) * 16 + wid * 2 + g;
;                 const long row = (long)pm * 256 + rloc;
;                 const u32x4 a = *(const u32x4*)(lds + rloc * 528 + j32 * 16);
;                 u32x4 w; float ss = 0.f;
; #pragma unroll
;                 for (int e = 0; e < 4; ++e) {
;                     w[e] = pk2(bflo(xv[u][e]) + bflo(a[e]), bfhi(xv[u][e]) + bfhi(a[e]));
;                     const float b0 = bflo(w[e]), b1 = bfhi(w[e]);
;                     ss += b0 * b0 + b1 * b1;
;                 }
;                 *(u32x4*)(xnew + row * 1024 + pn * 256 + j32 * 8) = w;
; #pragma unroll
;                 for (int o = 1; o < 32; o <<= 1) ss += __shfl_xor(ss, o);
;                 if (j32 == 0) ssq[row * 4 + pn] = ss;
	v_cvt_pk_bf16_f32 v33, v34, v35
	v_cvt_pk_bf16_f32 v28, v28, v29
	v_cvt_pk_bf16_f32 v29, v30, v31
	v_cvt_pk_bf16_f32 v24, v24, v25
	v_cvt_pk_bf16_f32 v25, v26, v27
	v_add_u32_e32 v26, 0xc000, v138
	v_cvt_pk_bf16_f32 v20, v20, v21
	v_cvt_pk_bf16_f32 v21, v22, v23
	v_cvt_pk_bf16_f32 v16, v16, v17
	v_cvt_pk_bf16_f32 v17, v18, v19
	v_cvt_pk_bf16_f32 v12, v12, v13
	v_cvt_pk_bf16_f32 v13, v14, v15
	v_cvt_pk_bf16_f32 v8, v8, v9
	v_cvt_pk_bf16_f32 v9, v10, v11
	v_add_u32_e32 v10, 0xe000, v138
	v_cvt_pk_bf16_f32 v4, v4, v5
	v_cvt_pk_bf16_f32 v5, v6, v7
	v_cvt_pk_bf16_f32 v0, v0, v1
	v_cvt_pk_bf16_f32 v1, v2, v3
	ds_write2_b64 v138, v[124:125], v[120:121] offset1:4
	ds_write2_b64 v138, v[116:117], v[112:113] offset0:8 offset1:12
	ds_write2_b64 v106, v[108:109], v[104:105] offset0:32 offset1:36
	ds_write2_b64 v106, v[100:101], v[96:97] offset0:40 offset1:44
	ds_write2_b64 v90, v[92:93], v[88:89] offset0:64 offset1:68
	ds_write2_b64 v90, v[84:85], v[80:81] offset0:72 offset1:76
	ds_write2_b64 v74, v[76:77], v[72:73] offset0:96 offset1:100
	ds_write2_b64 v74, v[68:69], v[64:65] offset0:104 offset1:108
	ds_write2_b64 v58, v[60:61], v[56:57] offset0:128 offset1:132
	ds_write2_b64 v58, v[52:53], v[48:49] offset0:136 offset1:140
	ds_write2_b64 v42, v[44:45], v[40:41] offset0:160 offset1:164
	ds_write2_b64 v42, v[36:37], v[32:33] offset0:168 offset1:172
	ds_write2_b64 v26, v[28:29], v[24:25] offset0:192 offset1:196
	ds_write2_b64 v26, v[20:21], v[16:17] offset0:200 offset1:204
	ds_write2_b64 v10, v[12:13], v[8:9] offset0:224 offset1:228
	ds_write2_b64 v10, v[4:5], v[0:1] offset0:232 offset1:236
	s_waitcnt lgkmcnt(0)
	s_barrier
	v_ashrrev_i32_e32 v0, 5, v136
	v_ashrrev_i32_e32 v1, 5, v137
	v_and_b32_e32 v14, 31, v136
	v_and_b32_e32 v2, -2, v1
	v_ashrrev_i32_e32 v1, 31, v0
	v_ashrrev_i32_e32 v3, 31, v2
	v_lshl_add_u64 v[4:5], s[12:13], 0, v[0:1]
	s_lshl_b32 s16, s6, 8
	v_add_u32_e32 v16, v2, v0
	v_lshlrev_b32_e32 v146, 4, v14
	v_and_b32_e32 v0, 64, v169
	v_lshl_add_u64 v[4:5], v[4:5], 0, v[2:3]
	s_ashr_i32 s17, s16, 31
	v_add_u32_e32 v26, 0, v146
	v_add_u32_e32 v15, 64, v0
	v_cmp_eq_u32_e64 s[4:5], 0, v14
	v_cmp_eq_u32_e64 s[98:99], 16, v14
	s_lshl_b64 s[18:19], s[16:17], 1
	s_add_u32 s22, s10, s18
	s_addc_u32 s23, s11, s19
	v_lshl_add_u64 v[0:1], s[22:23], 0, v[146:147]
	v_lshlrev_b64 v[2:3], 11, v[4:5]
	v_lshl_add_u64 v[18:19], v[0:1], 0, v[2:3]
	flat_load_dwordx4 v[22:25], v[18:19]
	v_add_co_u32_e32 v0, vcc, s49, v18
	v_mul_lo_u32 v20, v16, s3
	s_nop 0
	v_addc_co_u32_e32 v1, vcc, 0, v19, vcc
	flat_load_dwordx4 v[8:11], v[0:1]
	v_add_co_u32_e32 v0, vcc, s48, v18
	v_add_u32_e32 v12, v26, v20
	s_nop 0
	v_addc_co_u32_e32 v1, vcc, 0, v19, vcc
	flat_load_dwordx4 v[4:7], v[0:1]
	v_add_co_u32_e32 v0, vcc, s47, v18
	ds_read_b128 v[28:31], v12
	s_nop 0
	v_addc_co_u32_e32 v1, vcc, 0, v19, vcc
	flat_load_dwordx4 v[0:3], v[0:1]
	v_ashrrev_i32_e32 v17, 31, v16
	s_waitcnt lgkmcnt(0)
	v_lshlrev_b32_e32 v32, 16, v28
	v_and_b32_e32 v33, 0xffff0000, v28
	v_lshlrev_b32_e32 v28, 16, v29
	v_and_b32_e32 v29, 0xffff0000, v29
	s_waitcnt vmcnt(0)
	v_lshlrev_b32_e32 v12, 16, v22
	v_and_b32_e32 v13, 0xffff0000, v22
	v_pk_add_f32 v[12:13], v[12:13], v[32:33]
	s_nop 0
	v_cvt_pk_bf16_f32 v22, v12, v13
	v_and_b32_e32 v13, 0xffff0000, v22
	v_lshlrev_b32_e32 v12, 16, v22
	v_mul_f32_e32 v21, v13, v13
	v_fmac_f32_e32 v21, v12, v12
	v_lshlrev_b32_e32 v12, 16, v23
	v_and_b32_e32 v13, 0xffff0000, v23
	v_pk_add_f32 v[12:13], v[12:13], v[28:29]
	v_lshlrev_b32_e32 v28, 16, v30
	v_cvt_pk_bf16_f32 v23, v12, v13
	v_and_b32_e32 v13, 0xffff0000, v23
	v_lshlrev_b32_e32 v12, 16, v23
	v_mul_f32_e32 v13, v13, v13
	v_fmac_f32_e32 v13, v12, v12
	v_add_f32_e32 v21, v21, v13
	v_lshlrev_b32_e32 v12, 16, v24
	v_and_b32_e32 v13, 0xffff0000, v24
	v_and_b32_e32 v29, 0xffff0000, v30
	v_pk_add_f32 v[12:13], v[12:13], v[28:29]
	v_lshlrev_b32_e32 v28, 16, v31
	v_cvt_pk_bf16_f32 v24, v12, v13
	v_and_b32_e32 v13, 0xffff0000, v24
	v_lshlrev_b32_e32 v12, 16, v24
	v_mul_f32_e32 v13, v13, v13
	v_fmac_f32_e32 v13, v12, v12
	v_add_f32_e32 v21, v13, v21
	v_lshlrev_b32_e32 v12, 16, v25
	v_and_b32_e32 v13, 0xffff0000, v25
	v_and_b32_e32 v29, 0xffff0000, v31
	v_pk_add_f32 v[12:13], v[12:13], v[28:29]
	s_nop 0
	v_cvt_pk_bf16_f32 v25, v12, v13
	v_and_b32_e32 v13, 0xffff0000, v25
	v_lshlrev_b32_e32 v12, 16, v25
	v_mul_f32_e32 v13, v13, v13
	v_fmac_f32_e32 v13, v12, v12
	v_add_f32_e32 v21, v13, v21
	v_lshl_add_u64 v[12:13], s[12:13], 0, v[16:17]
	v_lshlrev_b64 v[28:29], 11, v[12:13]
	v_xor_b32_e32 v17, 1, v169
	v_lshl_add_u64 v[28:29], s[68:69], 0, v[28:29]
	v_cmp_lt_i32_e32 vcc, v17, v15
	v_lshl_add_u64 v[28:29], v[28:29], 0, s[18:19]
	v_lshl_add_u64 v[28:29], v[28:29], 0, v[146:147]
	v_cndmask_b32_e32 v17, v169, v17, vcc
	v_lshlrev_b32_e32 v17, 2, v17
	flat_store_dwordx4 v[28:29], v[22:25]
	s_nop 1
	v_add_f32_dpp v86, v21, v21 quad_perm:[1,0,3,2] row_mask:0xf bank_mask:0xf
	s_nop 1
	v_add_f32_dpp v86, v86, v86 quad_perm:[2,3,0,1] row_mask:0xf bank_mask:0xf
	s_nop 1
	v_add_f32_dpp v86, v86, v86 row_half_mirror row_mask:0xf bank_mask:0xf
	s_nop 1
	v_add_f32_dpp v86, v86, v86 row_mirror row_mask:0xf bank_mask:0xf
	s_nop 1
	v_add_f32_dpp v86, v86, v86 row_bcast:15 row_mask:0xa bank_mask:0xf
	s_waitcnt lgkmcnt(0)
	v_xor_b32_e32 v22, 2, v169
	v_cmp_lt_i32_e32 vcc, v22, v15
	s_nop 1
	v_cndmask_b32_e32 v22, v169, v22, vcc
	v_lshlrev_b32_e32 v22, 2, v22
	s_waitcnt lgkmcnt(0)
	v_xor_b32_e32 v23, 4, v169
	v_cmp_lt_i32_e32 vcc, v23, v15
	s_nop 1
	v_cndmask_b32_e32 v23, v169, v23, vcc
	v_lshlrev_b32_e32 v23, 2, v23
	s_waitcnt lgkmcnt(0)
	v_xor_b32_e32 v24, 8, v169
	v_cmp_lt_i32_e32 vcc, v24, v15
	s_nop 1
	v_cndmask_b32_e32 v24, v169, v24, vcc
	v_lshlrev_b32_e32 v24, 2, v24
	s_waitcnt lgkmcnt(0)
	v_xor_b32_e32 v25, 16, v169
	v_cmp_lt_i32_e32 vcc, v25, v15
	s_nop 1
	v_cndmask_b32_e32 v15, v169, v25, vcc
	v_lshlrev_b32_e32 v25, 2, v15
	s_and_saveexec_b64 s[18:19], s[98:99]
	s_cbranch_execz .LBB0_526
	v_lshl_add_u64 v[12:13], v[12:13], 4, s[78:79]
	v_lshl_add_u64 v[12:13], s[6:7], 2, v[12:13]
	s_waitcnt lgkmcnt(0)
	v_mov_b32_e32 v15, v86
	flat_store_dword v[12:13], v15

; #define MFMA16(a, b, c) __builtin_amdgcn_mfma_f32_16x16x32_bf16((a), (b), (c), 0, 0, 0)
; DI bf16x8 ldfrag(const char* lds, int row, int chunk) { return *(const bf16x8*)(lds + swz(row, chunk)); }
; template <bool RSTD, bool SWAP>
; DI void gemm_tile(gacc_t& acc, const bf16_t* __restrict__ A, int lda, const bf16_t* __restrict__ Bt, int ldb, int K,
;                   char* lds, int tid, int wr, int wc, int lane, const float* ssq_row) {
;     ...
;     GEMM_ISSUE(0, 0);
;     if (RSTD && tid < 256) {
;         const f32x4 q = *(const f32x4*)ssq_row;
;         ((float*)(lds + RSTD_OFF))[tid] = 1.0f / sqrtf(((q.x + q.y) + (q.z + q.w)) * (1.0f / 1024.0f) + 1e-6f);
;     }
;     asm volatile("s_waitcnt vmcnt(0)" ::: "memory");
;     __syncthreads();
;     for (int kt = 0; kt < nk; ++kt) {
;         const char* cur = lds + (kt & 1) * 65536;
;         if (kt + 1 < nk) GEMM_ISSUE(kt + 1, (kt + 1) & 1);
;         bf16x8 bfr[2][4], afr[3];
; #pragma unroll
;         for (int n = 0; n < 4; ++n) bfr[0][n] = ldfrag(cur + 32768, wc * 64 + n * 16 + fr, fq);
;         afr[0] = ldfrag(cur, wr * 128 + fr, fq);
;         afr[1] = ldfrag(cur, wr * 128 + 16 + fr, fq);
; #pragma unroll
;         for (int idx = 0; idx < 16; ++idx) {
;             const int ks = idx >> 3, m = idx & 7;
;             if (idx < 14) afr[(idx + 2) % 3] = ldfrag(cur, wr * 128 + ((idx + 2) & 7) * 16 + fr, ((idx + 2) >> 3) * 4 + fq);
;             if (ks == 0 && m >= 2 && m < 6) bfr[1][m - 2] = ldfrag(cur + 32768, wc * 64 + (m - 2) * 16 + fr, 4 + fq);
; #pragma unroll
;             for (int n = 0; n < 4; ++n) acc[m][n] = SWAP ? MFMA16(bfr[ks][n], afr[idx % 3], acc[m][n]) : MFMA16(afr[idx % 3], bfr[ks][n], acc[m][n]);
.LBB0_775:
	s_add_i32 s16, s13, 0xffff0000
	v_lshl_add_u64 v[156:157], v[138:139], 0, s[4:5]
	s_and_b32 s18, s13, 0x10000
	s_and_b32 s21, s16, 0x10000
	s_mov_b64 s[16:17], 0x10080080
	v_lshl_add_u64 v[158:159], v[136:137], 0, s[4:5]
	v_lshl_add_u64 v[160:161], v[156:157], 0, s[16:17]
	s_add_i32 s16, s18, 0
	s_mov_b64 s[18:19], 0x4880080
	v_lshl_add_u64 v[162:163], v[158:159], 0, s[18:19]
	s_mov_b64 s[18:19], 0x100d8080
	v_lshl_add_u64 v[164:165], v[156:157], 0, s[18:19]
	s_mov_b64 s[18:19], 0x48d8080
	v_lshl_add_u64 v[166:167], v[158:159], 0, s[18:19]
	s_mov_b64 s[18:19], 0x10130080
	v_lshl_add_u64 v[172:173], v[156:157], 0, s[18:19]
	s_mov_b64 s[18:19], 0x4930080
	v_lshl_add_u64 v[174:175], v[158:159], 0, s[18:19]
	s_mov_b64 s[18:19], 0x10188080
	v_lshl_add_u64 v[156:157], v[156:157], 0, s[18:19]
	s_mov_b64 s[18:19], 0x4988080
	v_lshl_add_u64 v[158:159], v[158:159], 0, s[18:19]
	s_add_i32 s18, s16, s12
	s_add_i32 s19, s18, 0x8000
	s_mov_b32 m0, s18
	s_add_i32 s17, s21, 0
	global_load_lds_dwordx4 v[160:161], off
	v_mfma_f32_16x16x32_bf16 v[60:63], v[190:193], v[236:239], v[60:63]
	s_mov_b32 m0, s19
	v_add_u32_e32 v146, s17, v142
	global_load_lds_dwordx4 v[162:163], off
	v_mfma_f32_16x16x32_bf16 v[56:59], v[194:197], v[236:239], v[56:59]
	s_add_i32 m0, s18, 0x2000
	v_add3_u32 v155, v146, v148, v149
	global_load_lds_dwordx4 v[164:165], off
	v_mfma_f32_16x16x32_bf16 v[52:55], v[198:201], v[236:239], v[52:55]
	s_add_i32 m0, s18, 0xa000
	v_add_u32_e32 v185, v146, v144
	global_load_lds_dwordx4 v[166:167], off
	v_mfma_f32_16x16x32_bf16 v[48:51], v[202:205], v[236:239], v[48:51]
	s_add_i32 m0, s18, 0x4000
	v_mfma_f32_16x16x32_bf16 v[44:47], v[190:193], v[240:243], v[44:47]
	global_load_lds_dwordx4 v[172:173], off
	s_add_i32 m0, s18, 0xc000
	v_mfma_f32_16x16x32_bf16 v[40:43], v[194:197], v[240:243], v[40:43]
	global_load_lds_dwordx4 v[174:175], off
	s_add_i32 m0, s18, 0x6000
	v_mfma_f32_16x16x32_bf16 v[36:39], v[198:201], v[240:243], v[36:39]
	global_load_lds_dwordx4 v[156:157], off
	s_add_i32 m0, s18, 0xe000
	v_mfma_f32_16x16x32_bf16 v[32:35], v[202:205], v[240:243], v[32:35]
	global_load_lds_dwordx4 v[158:159], off
	ds_read_b128 v[156:159], v155 offset:32768
	ds_read_b128 v[160:163], v155 offset:34816
	ds_read_b128 v[172:175], v155 offset:36864
	ds_read_b128 v[176:179], v155 offset:38912
	ds_read_b128 v[164:167], v185
	ds_read_b128 v[180:183], v185 offset:2048
	v_add_u32_e32 v155, v146, v150
	ds_read_b128 v[186:189], v185 offset:4096
	v_mfma_f32_16x16x32_bf16 v[28:31], v[190:193], v[244:247], v[28:31]
	v_mfma_f32_16x16x32_bf16 v[24:27], v[194:197], v[244:247], v[24:27]
	v_mfma_f32_16x16x32_bf16 v[20:23], v[198:201], v[244:247], v[20:23]
	v_mfma_f32_16x16x32_bf16 v[16:19], v[202:205], v[244:247], v[16:19]
	v_mfma_f32_16x16x32_bf16 v[12:15], v[190:193], v[248:251], v[12:15]
	v_mfma_f32_16x16x32_bf16 v[8:11], v[194:197], v[248:251], v[8:11]
	v_mfma_f32_16x16x32_bf16 v[4:7], v[198:201], v[248:251], v[4:7]
	v_mfma_f32_16x16x32_bf16 v[0:3], v[202:205], v[248:251], v[0:3]
	s_waitcnt lgkmcnt(2)
	v_mfma_f32_16x16x32_bf16 v[124:127], v[156:159], v[164:167], v[124:127]
	v_add_u32_e32 v146, v146, v152
	v_mfma_f32_16x16x32_bf16 v[120:123], v[160:163], v[164:167], v[120:123]
	v_mfma_f32_16x16x32_bf16 v[116:119], v[172:175], v[164:167], v[116:119]
	v_mfma_f32_16x16x32_bf16 v[112:115], v[176:179], v[164:167], v[112:115]
	ds_read_b128 v[164:167], v155
	v_add_u32_e32 v155, s17, v145
	v_add_u32_e32 v198, v155, v151
	s_waitcnt lgkmcnt(2)
	v_mfma_f32_16x16x32_bf16 v[108:111], v[156:159], v[180:183], v[108:111]
	v_mfma_f32_16x16x32_bf16 v[104:107], v[160:163], v[180:183], v[104:107]
	v_mfma_f32_16x16x32_bf16 v[100:103], v[172:175], v[180:183], v[100:103]
	v_mfma_f32_16x16x32_bf16 v[96:99], v[176:179], v[180:183], v[96:99]
	ds_read_b128 v[180:183], v185 offset:8192
	ds_read_b128 v[190:193], v198 offset:32768
	s_waitcnt lgkmcnt(3)
	v_mfma_f32_16x16x32_bf16 v[92:95], v[156:159], v[186:189], v[92:95]
	v_mfma_f32_16x16x32_bf16 v[88:91], v[160:163], v[186:189], v[88:91]
	v_mfma_f32_16x16x32_bf16 v[84:87], v[172:175], v[186:189], v[84:87]
	v_mfma_f32_16x16x32_bf16 v[80:83], v[176:179], v[186:189], v[80:83]
	ds_read_b128 v[186:189], v185 offset:10240
	ds_read_b128 v[194:197], v198 offset:34816
	s_waitcnt lgkmcnt(4)
	v_mfma_f32_16x16x32_bf16 v[76:79], v[156:159], v[164:167], v[76:79]
	v_mfma_f32_16x16x32_bf16 v[72:75], v[160:163], v[164:167], v[72:75]
	v_mfma_f32_16x16x32_bf16 v[68:71], v[172:175], v[164:167], v[68:71]
	v_mfma_f32_16x16x32_bf16 v[64:67], v[176:179], v[164:167], v[64:67]
	ds_read_b128 v[164:167], v185 offset:12288
	v_add_u32_e32 v185, v155, v153
	ds_read_b128 v[198:201], v198 offset:36864
	s_waitcnt lgkmcnt(5)
	v_mfma_f32_16x16x32_bf16 v[60:63], v[156:159], v[180:183], v[60:63]
	v_mfma_f32_16x16x32_bf16 v[56:59], v[160:163], v[180:183], v[56:59]
	v_mfma_f32_16x16x32_bf16 v[52:55], v[172:175], v[180:183], v[52:55]
	v_mfma_f32_16x16x32_bf16 v[48:51], v[176:179], v[180:183], v[48:51]
	ds_read_b128 v[202:205], v185 offset:38912
	ds_read_b128 v[180:183], v146
	v_add_u32_e32 v146, v155, v144
	s_waitcnt lgkmcnt(5)
	v_mfma_f32_16x16x32_bf16 v[44:47], v[156:159], v[186:189], v[44:47]
	v_mfma_f32_16x16x32_bf16 v[40:43], v[160:163], v[186:189], v[40:43]
	v_mfma_f32_16x16x32_bf16 v[36:39], v[172:175], v[186:189], v[36:39]
	v_mfma_f32_16x16x32_bf16 v[32:35], v[176:179], v[186:189], v[32:35]
	ds_read_b128 v[186:189], v146
	s_waitcnt lgkmcnt(4)
	v_mfma_f32_16x16x32_bf16 v[28:31], v[156:159], v[164:167], v[28:31]
	v_mfma_f32_16x16x32_bf16 v[24:27], v[160:163], v[164:167], v[24:27]
	v_mfma_f32_16x16x32_bf16 v[20:23], v[172:175], v[164:167], v[20:23]
	v_mfma_f32_16x16x32_bf16 v[16:19], v[176:179], v[164:167], v[16:19]
	ds_read_b128 v[164:167], v146 offset:2048
	s_waitcnt lgkmcnt(2)
; #define MFMA16(a, b, c) __builtin_amdgcn_mfma_f32_16x16x32_bf16((a), (b), (c), 0, 0, 0)
; DI bf16x8 ldfrag(const char* lds, int row, int chunk) { return *(const bf16x8*)(lds + swz(row, chunk)); }
; #define GEMM_SG1() do { __builtin_amdgcn_sched_group_barrier(0x100, 1, 0); __builtin_amdgcn_sched_group_barrier(0x008, 4, 0); } while (0)
; #define GEMM_SG2() do { __builtin_amdgcn_sched_group_barrier(0x100, 2, 0); __builtin_amdgcn_sched_group_barrier(0x008, 4, 0); } while (0)
; template <bool RSTD, bool SWAP>
; DI void gemm_tile(gacc_t& acc, const bf16_t* __restrict__ A, int lda, const bf16_t* __restrict__ Bt, int ldb, int K,
;                   char* lds, int tid, int wr, int wc, int lane, const float* ssq_row) {
;     ...
;     for (int kt = 0; kt < nk; ++kt) {
;         const char* cur = lds + (kt & 1) * 65536;
;         if (kt + 1 < nk) GEMM_ISSUE(kt + 1, (kt + 1) & 1);
;         bf16x8 bfr[2][4], afr[3];
; #pragma unroll
;         for (int n = 0; n < 4; ++n) bfr[0][n] = ldfrag(cur + 32768, wc * 64 + n * 16 + fr, fq);
;         afr[0] = ldfrag(cur, wr * 128 + fr, fq);
;         afr[1] = ldfrag(cur, wr * 128 + 16 + fr, fq);
; #pragma unroll
;         for (int idx = 0; idx < 16; ++idx) {
;             const int ks = idx >> 3, m = idx & 7;
;             if (idx < 14) afr[(idx + 2) % 3] = ldfrag(cur, wr * 128 + ((idx + 2) & 7) * 16 + fr, ((idx + 2) >> 3) * 4 + fq);
;             if (ks == 0 && m >= 2 && m < 6) bfr[1][m - 2] = ldfrag(cur + 32768, wc * 64 + (m - 2) * 16 + fr, 4 + fq);
; #pragma unroll
;             for (int n = 0; n < 4; ++n) acc[m][n] = SWAP ? MFMA16(bfr[ks][n], afr[idx % 3], acc[m][n]) : MFMA16(afr[idx % 3], bfr[ks][n], acc[m][n]);
;         }
;         __builtin_amdgcn_sched_group_barrier(0x100, 6, 0);
;     ...
;         GEMM_SG1(); GEMM_SG1(); GEMM_SG2(); GEMM_SG2(); GEMM_SG2(); GEMM_SG2(); GEMM_SG1(); GEMM_SG1();
;         GEMM_SG1(); GEMM_SG1(); GEMM_SG1(); GEMM_SG1(); GEMM_SG1(); GEMM_SG1();
;         __builtin_amdgcn_sched_group_barrier(0x008, 8, 0);
;         __builtin_amdgcn_sched_barrier(0);
;         asm volatile("s_waitcnt vmcnt(0)" ::: "memory");
;         __syncthreads();
;     }
	v_mfma_f32_16x16x32_bf16 v[8:11], v[160:163], v[180:183], v[8:11]
	v_add_u32_e32 v160, v155, v150
	v_mfma_f32_16x16x32_bf16 v[12:15], v[156:159], v[180:183], v[12:15]
	v_mfma_f32_16x16x32_bf16 v[4:7], v[172:175], v[180:183], v[4:7]
	v_mfma_f32_16x16x32_bf16 v[0:3], v[176:179], v[180:183], v[0:3]
	ds_read_b128 v[156:159], v146 offset:4096
	s_waitcnt lgkmcnt(2)
	v_mfma_f32_16x16x32_bf16 v[124:127], v[190:193], v[186:189], v[124:127]
	v_mfma_f32_16x16x32_bf16 v[120:123], v[194:197], v[186:189], v[120:123]
	v_mfma_f32_16x16x32_bf16 v[116:119], v[198:201], v[186:189], v[116:119]
	v_mfma_f32_16x16x32_bf16 v[112:115], v[202:205], v[186:189], v[112:115]
	ds_read_b128 v[160:163], v160
	s_waitcnt lgkmcnt(2)
	v_mfma_f32_16x16x32_bf16 v[108:111], v[190:193], v[164:167], v[108:111]
	v_mfma_f32_16x16x32_bf16 v[104:107], v[194:197], v[164:167], v[104:107]
	v_mfma_f32_16x16x32_bf16 v[100:103], v[198:201], v[164:167], v[100:103]
	v_mfma_f32_16x16x32_bf16 v[96:99], v[202:205], v[164:167], v[96:99]
	ds_read_b128 v[236:239], v146 offset:8192
	s_waitcnt lgkmcnt(2)
	v_mfma_f32_16x16x32_bf16 v[92:95], v[190:193], v[156:159], v[92:95]
	v_mfma_f32_16x16x32_bf16 v[88:91], v[194:197], v[156:159], v[88:91]
	v_mfma_f32_16x16x32_bf16 v[84:87], v[198:201], v[156:159], v[84:87]
	v_mfma_f32_16x16x32_bf16 v[80:83], v[202:205], v[156:159], v[80:83]
	ds_read_b128 v[240:243], v146 offset:10240
	ds_read_b128 v[244:247], v146 offset:12288
	v_add_u32_e32 v146, v155, v152
	ds_read_b128 v[248:251], v146
	s_waitcnt lgkmcnt(4)
	v_mfma_f32_16x16x32_bf16 v[76:79], v[190:193], v[160:163], v[76:79]
	v_mfma_f32_16x16x32_bf16 v[72:75], v[194:197], v[160:163], v[72:75]
	v_mfma_f32_16x16x32_bf16 v[68:71], v[198:201], v[160:163], v[68:71]
	v_mfma_f32_16x16x32_bf16 v[64:67], v[202:205], v[160:163], v[64:67]
	s_waitcnt lgkmcnt(0)
	s_waitcnt vmcnt(0)
	s_add_u32 s4, s4, 0x80
	s_addc_u32 s5, s5, 0
	s_add_i32 s13, s13, 0x10000
	s_cmpk_eq_i32 s4, 0x1580
	s_waitcnt vmcnt(0)
	s_cbranch_scc0 .Lkhead_775
	s_barrier
	v_mfma_f32_16x16x32_bf16 v[60:63], v[190:193], v[236:239], v[60:63]
	v_mfma_f32_16x16x32_bf16 v[56:59], v[194:197], v[236:239], v[56:59]
	v_mfma_f32_16x16x32_bf16 v[52:55], v[198:201], v[236:239], v[52:55]
	v_mfma_f32_16x16x32_bf16 v[48:51], v[202:205], v[236:239], v[48:51]
	v_mfma_f32_16x16x32_bf16 v[44:47], v[190:193], v[240:243], v[44:47]
	v_mfma_f32_16x16x32_bf16 v[40:43], v[194:197], v[240:243], v[40:43]
	v_mfma_f32_16x16x32_bf16 v[36:39], v[198:201], v[240:243], v[36:39]
	v_mfma_f32_16x16x32_bf16 v[32:35], v[202:205], v[240:243], v[32:35]
	v_mfma_f32_16x16x32_bf16 v[28:31], v[190:193], v[244:247], v[28:31]
	v_mfma_f32_16x16x32_bf16 v[24:27], v[194:197], v[244:247], v[24:27]
	v_mfma_f32_16x16x32_bf16 v[20:23], v[198:201], v[244:247], v[20:23]
	v_mfma_f32_16x16x32_bf16 v[16:19], v[202:205], v[244:247], v[16:19]
	v_mfma_f32_16x16x32_bf16 v[12:15], v[190:193], v[248:251], v[12:15]
	v_mfma_f32_16x16x32_bf16 v[8:11], v[194:197], v[248:251], v[8:11]
	v_mfma_f32_16x16x32_bf16 v[4:7], v[198:201], v[248:251], v[4:7]
	v_mfma_f32_16x16x32_bf16 v[0:3], v[202:205], v[248:251], v[0:3]
	v_add_u32_e32 v146, s16, v142
	v_add3_u32 v155, v146, v148, v149
	ds_read_b128 v[136:139], v155 offset:32768
	ds_read_b128 v[156:159], v155 offset:34816
	ds_read_b128 v[164:167], v155 offset:36864
	ds_read_b128 v[172:175], v155 offset:38912
	v_add_u32_e32 v185, v146, v144
	ds_read_b128 v[160:163], v185
	ds_read_b128 v[176:179], v185 offset:2048
	v_add_u32_e32 v155, v146, v150
	ds_read_b128 v[180:183], v185 offset:4096
	s_waitcnt lgkmcnt(2)
	v_mfma_f32_16x16x32_bf16 v[124:127], v[136:139], v[160:163], v[124:127]
	v_add_u32_e32 v146, v146, v152
	s_lshl_b64 s[12:13], s[8:9], 8
	v_mfma_f32_16x16x32_bf16 v[120:123], v[156:159], v[160:163], v[120:123]
	v_mfma_f32_16x16x32_bf16 v[116:119], v[164:167], v[160:163], v[116:119]
	v_mfma_f32_16x16x32_bf16 v[112:115], v[172:175], v[160:163], v[112:115]
	ds_read_b128 v[160:163], v155
	v_add_u32_e32 v155, s16, v145
	v_add_u32_e32 v194, v155, v151
	s_waitcnt lgkmcnt(2)
	v_mfma_f32_16x16x32_bf16 v[108:111], v[136:139], v[176:179], v[108:111]
	v_mfma_f32_16x16x32_bf16 v[104:107], v[156:159], v[176:179], v[104:107]
	v_mfma_f32_16x16x32_bf16 v[100:103], v[164:167], v[176:179], v[100:103]
	v_mfma_f32_16x16x32_bf16 v[96:99], v[172:175], v[176:179], v[96:99]
	ds_read_b128 v[176:179], v185 offset:8192
	ds_read_b128 v[186:189], v194 offset:32768
	s_waitcnt lgkmcnt(3)
	v_mfma_f32_16x16x32_bf16 v[92:95], v[136:139], v[180:183], v[92:95]
	v_mfma_f32_16x16x32_bf16 v[88:91], v[156:159], v[180:183], v[88:91]
	v_mfma_f32_16x16x32_bf16 v[84:87], v[164:167], v[180:183], v[84:87]
	v_mfma_f32_16x16x32_bf16 v[80:83], v[172:175], v[180:183], v[80:83]
	ds_read_b128 v[180:183], v185 offset:10240
	ds_read_b128 v[190:193], v194 offset:34816
	s_waitcnt lgkmcnt(4)
	v_mfma_f32_16x16x32_bf16 v[76:79], v[136:139], v[160:163], v[76:79]
	v_mfma_f32_16x16x32_bf16 v[72:75], v[156:159], v[160:163], v[72:75]
	v_mfma_f32_16x16x32_bf16 v[68:71], v[164:167], v[160:163], v[68:71]
	v_mfma_f32_16x16x32_bf16 v[64:67], v[172:175], v[160:163], v[64:67]
	ds_read_b128 v[160:163], v185 offset:12288
	ds_read_b128 v[194:197], v194 offset:36864
	s_waitcnt lgkmcnt(5)
	v_mfma_f32_16x16x32_bf16 v[60:63], v[136:139], v[176:179], v[60:63]
	v_mfma_f32_16x16x32_bf16 v[56:59], v[156:159], v[176:179], v[56:59]
	v_mfma_f32_16x16x32_bf16 v[52:55], v[164:167], v[176:179], v[52:55]
	v_mfma_f32_16x16x32_bf16 v[48:51], v[172:175], v[176:179], v[48:51]
	ds_read_b128 v[176:179], v146
	v_add_u32_e32 v146, v155, v153
	ds_read_b128 v[198:201], v146 offset:38912
	v_add_u32_e32 v146, v155, v144
	s_waitcnt lgkmcnt(5)
; #define MFMA16(a, b, c) __builtin_amdgcn_mfma_f32_16x16x32_bf16((a), (b), (c), 0, 0, 0)
; DI unsigned pk2(float a, float b) { f32x2 v = {a, b}; bf16x2_t r = __builtin_convertvector(v, bf16x2_t); return __builtin_bit_cast(unsigned, r); }
; DI bf16x8 ldfrag(const char* lds, int row, int chunk) { return *(const bf16x8*)(lds + swz(row, chunk)); }
; template <bool RSTD, bool SWAP>
; DI void gemm_tile(gacc_t& acc, const bf16_t* __restrict__ A, int lda, const bf16_t* __restrict__ Bt, int ldb, int K,
;                   char* lds, int tid, int wr, int wc, int lane, const float* ssq_row) {
;     ...
;         for (int idx = 0; idx < 16; ++idx) {
;             const int ks = idx >> 3, m = idx & 7;
;             if (idx < 14) afr[(idx + 2) % 3] = ldfrag(cur, wr * 128 + ((idx + 2) & 7) * 16 + fr, ((idx + 2) >> 3) * 4 + fq);
;             if (ks == 0 && m >= 2 && m < 6) bfr[1][m - 2] = ldfrag(cur + 32768, wc * 64 + (m - 2) * 16 + fr, 4 + fq);
; #pragma unroll
;             for (int n = 0; n < 4; ++n) acc[m][n] = SWAP ? MFMA16(bfr[ks][n], afr[idx % 3], acc[m][n]) : MFMA16(afr[idx % 3], bfr[ks][n], acc[m][n]);
;     DI void operator()(gacc_t& acc, int pm, int pn, char* lds, int tid, int wr, int wc, int lane) const {
;     ...
;         char* lbase = lds + (wr * 128 + fr) * 528 + (wc * 64 + 4 * fq) * 2;
; #pragma unroll
;         for (int m = 0; m < 8; ++m)
; #pragma unroll
;             for (int n = 0; n < 4; ++n) { u32x2 w; w.x = pk2(acc[m][n][0], acc[m][n][1]); w.y = pk2(acc[m][n][2], acc[m][n][3]); *(u32x2*)(lbase + m * 16 * 528 + n * 32) = w; }
	v_mfma_f32_16x16x32_bf16 v[44:47], v[136:139], v[180:183], v[44:47]
	v_mfma_f32_16x16x32_bf16 v[40:43], v[156:159], v[180:183], v[40:43]
	v_mfma_f32_16x16x32_bf16 v[36:39], v[164:167], v[180:183], v[36:39]
	v_mfma_f32_16x16x32_bf16 v[32:35], v[172:175], v[180:183], v[32:35]
	ds_read_b128 v[180:183], v146
	s_waitcnt lgkmcnt(4)
	v_mfma_f32_16x16x32_bf16 v[28:31], v[136:139], v[160:163], v[28:31]
	v_mfma_f32_16x16x32_bf16 v[24:27], v[156:159], v[160:163], v[24:27]
	v_mfma_f32_16x16x32_bf16 v[20:23], v[164:167], v[160:163], v[20:23]
	v_mfma_f32_16x16x32_bf16 v[16:19], v[172:175], v[160:163], v[16:19]
	ds_read_b128 v[160:163], v146 offset:2048
	s_waitcnt lgkmcnt(3)
	v_mfma_f32_16x16x32_bf16 v[8:11], v[156:159], v[176:179], v[8:11]
	v_add_u32_e32 v156, v155, v150
	v_mfma_f32_16x16x32_bf16 v[12:15], v[136:139], v[176:179], v[12:15]
	v_mfma_f32_16x16x32_bf16 v[4:7], v[164:167], v[176:179], v[4:7]
	v_mfma_f32_16x16x32_bf16 v[0:3], v[172:175], v[176:179], v[0:3]
	ds_read_b128 v[136:139], v146 offset:4096
	s_waitcnt lgkmcnt(2)
	v_mfma_f32_16x16x32_bf16 v[124:127], v[186:189], v[180:183], v[124:127]
	v_mfma_f32_16x16x32_bf16 v[120:123], v[190:193], v[180:183], v[120:123]
	v_mfma_f32_16x16x32_bf16 v[116:119], v[194:197], v[180:183], v[116:119]
	v_mfma_f32_16x16x32_bf16 v[112:115], v[198:201], v[180:183], v[112:115]
	ds_read_b128 v[156:159], v156
	s_waitcnt lgkmcnt(2)
	v_mfma_f32_16x16x32_bf16 v[108:111], v[186:189], v[160:163], v[108:111]
	v_mfma_f32_16x16x32_bf16 v[104:107], v[190:193], v[160:163], v[104:107]
	v_mfma_f32_16x16x32_bf16 v[100:103], v[194:197], v[160:163], v[100:103]
	v_mfma_f32_16x16x32_bf16 v[96:99], v[198:201], v[160:163], v[96:99]
	ds_read_b128 v[160:163], v146 offset:8192
	s_waitcnt lgkmcnt(2)
	v_mfma_f32_16x16x32_bf16 v[92:95], v[186:189], v[136:139], v[92:95]
	v_mfma_f32_16x16x32_bf16 v[88:91], v[190:193], v[136:139], v[88:91]
	v_mfma_f32_16x16x32_bf16 v[84:87], v[194:197], v[136:139], v[84:87]
	v_mfma_f32_16x16x32_bf16 v[80:83], v[198:201], v[136:139], v[80:83]
	ds_read_b128 v[136:139], v146 offset:10240
	s_waitcnt lgkmcnt(2)
	v_mfma_f32_16x16x32_bf16 v[76:79], v[186:189], v[156:159], v[76:79]
	v_mfma_f32_16x16x32_bf16 v[72:75], v[190:193], v[156:159], v[72:75]
	v_mfma_f32_16x16x32_bf16 v[68:71], v[194:197], v[156:159], v[68:71]
	v_mfma_f32_16x16x32_bf16 v[64:67], v[198:201], v[156:159], v[64:67]
	ds_read_b128 v[156:159], v146 offset:12288
	v_add_u32_e32 v146, v155, v152
	s_waitcnt lgkmcnt(2)
	v_mfma_f32_16x16x32_bf16 v[60:63], v[186:189], v[160:163], v[60:63]
	v_mfma_f32_16x16x32_bf16 v[56:59], v[190:193], v[160:163], v[56:59]
	v_mfma_f32_16x16x32_bf16 v[52:55], v[194:197], v[160:163], v[52:55]
	v_mfma_f32_16x16x32_bf16 v[48:51], v[198:201], v[160:163], v[48:51]
	ds_read_b128 v[160:163], v146
	s_waitcnt lgkmcnt(2)
	v_mfma_f32_16x16x32_bf16 v[44:47], v[186:189], v[136:139], v[44:47]
	v_mfma_f32_16x16x32_bf16 v[40:43], v[190:193], v[136:139], v[40:43]
	v_mfma_f32_16x16x32_bf16 v[36:39], v[194:197], v[136:139], v[36:39]
	v_mfma_f32_16x16x32_bf16 v[32:35], v[198:201], v[136:139], v[32:35]
	s_waitcnt lgkmcnt(1)
	v_mfma_f32_16x16x32_bf16 v[24:27], v[190:193], v[156:159], v[24:27]
	v_mfma_f32_16x16x32_bf16 v[20:23], v[194:197], v[156:159], v[20:23]
	v_mfma_f32_16x16x32_bf16 v[16:19], v[198:201], v[156:159], v[16:19]
	s_waitcnt lgkmcnt(0)
	v_mfma_f32_16x16x32_bf16 v[12:15], v[186:189], v[160:163], v[12:15]
	v_mfma_f32_16x16x32_bf16 v[8:11], v[190:193], v[160:163], v[8:11]
	v_mfma_f32_16x16x32_bf16 v[4:7], v[194:197], v[160:163], v[4:7]
	v_mfma_f32_16x16x32_bf16 v[0:3], v[198:201], v[160:163], v[0:3]
	v_mfma_f32_16x16x32_bf16 v[28:31], v[186:189], v[156:159], v[28:31]
	v_mov_b32_e32 v136, v140
	v_mov_b32_e32 v137, v141
	s_waitcnt vmcnt(0)
	s_barrier
	v_cvt_pk_bf16_f32 v124, v124, v125
	v_and_or_b32 v138, v137, 15, v143
	v_ashrrev_i32_e32 v139, 1, v137
	v_mul_lo_u32 v138, v138, s3
	v_and_b32_e32 v139, -8, v139
	v_add3_u32 v138, v154, v138, v139
	v_cvt_pk_bf16_f32 v125, v126, v127
	v_cvt_pk_bf16_f32 v120, v120, v121
	v_cvt_pk_bf16_f32 v121, v122, v123
	v_cvt_pk_bf16_f32 v116, v116, v117
	v_cvt_pk_bf16_f32 v117, v118, v119
	v_cvt_pk_bf16_f32 v112, v112, v113
	v_cvt_pk_bf16_f32 v113, v114, v115
	v_cvt_pk_bf16_f32 v108, v108, v109
	v_cvt_pk_bf16_f32 v109, v110, v111
	v_cvt_pk_bf16_f32 v104, v104, v105
	v_cvt_pk_bf16_f32 v105, v106, v107
	v_add_u32_e32 v106, 0x2000, v138
	v_cvt_pk_bf16_f32 v100, v100, v101
	v_cvt_pk_bf16_f32 v101, v102, v103
	v_cvt_pk_bf16_f32 v96, v96, v97
	v_cvt_pk_bf16_f32 v97, v98, v99
	v_cvt_pk_bf16_f32 v92, v92, v93
	v_cvt_pk_bf16_f32 v93, v94, v95
	v_cvt_pk_bf16_f32 v88, v88, v89
	v_cvt_pk_bf16_f32 v89, v90, v91
	v_add_u32_e32 v90, 0x4000, v138
	v_cvt_pk_bf16_f32 v84, v84, v85
	v_cvt_pk_bf16_f32 v85, v86, v87
	v_cvt_pk_bf16_f32 v80, v80, v81
	v_cvt_pk_bf16_f32 v81, v82, v83
	v_cvt_pk_bf16_f32 v76, v76, v77
	v_cvt_pk_bf16_f32 v77, v78, v79
	v_cvt_pk_bf16_f32 v72, v72, v73
	v_cvt_pk_bf16_f32 v73, v74, v75
	v_add_u32_e32 v74, 0x6000, v138
	v_cvt_pk_bf16_f32 v68, v68, v69
	v_cvt_pk_bf16_f32 v69, v70, v71
	v_cvt_pk_bf16_f32 v64, v64, v65
	v_cvt_pk_bf16_f32 v65, v66, v67
	v_cvt_pk_bf16_f32 v60, v60, v61
	v_cvt_pk_bf16_f32 v61, v62, v63
	v_cvt_pk_bf16_f32 v56, v56, v57
	v_cvt_pk_bf16_f32 v57, v58, v59
	v_add_u32_e32 v58, 0x8000, v138
	v_cvt_pk_bf16_f32 v52, v52, v53
	v_cvt_pk_bf16_f32 v53, v54, v55
	v_cvt_pk_bf16_f32 v48, v48, v49
	v_cvt_pk_bf16_f32 v49, v50, v51
	v_cvt_pk_bf16_f32 v44, v44, v45
	v_cvt_pk_bf16_f32 v45, v46, v47
	v_cvt_pk_bf16_f32 v40, v40, v41
	v_cvt_pk_bf16_f32 v41, v42, v43
	v_add_u32_e32 v42, 0xa000, v138
	v_cvt_pk_bf16_f32 v36, v36, v37
	v_cvt_pk_bf16_f32 v37, v38, v39
	v_cvt_pk_bf16_f32 v32, v32, v33
; DI unsigned pk2(float a, float b) { f32x2 v = {a, b}; bf16x2_t r = __builtin_convertvector(v, bf16x2_t); return __builtin_bit_cast(unsigned, r); }
; DI float bflo(unsigned w) { return __uint_as_float(w << 16); }
; DI float bfhi(unsigned w) { return __uint_as_float(w & 0xffff0000u); }
;     DI void operator()(gacc_t& acc, int pm, int pn, char* lds, int tid, int wr, int wc, int lane) const {
;     ...
;             for (int n = 0; n < 4; ++n) { u32x2 w; w.x = pk2(acc[m][n][0], acc[m][n][1]); w.y = pk2(acc[m][n][2], acc[m][n][3]); *(u32x2*)(lbase + m * 16 * 528 + n * 32) = w; }
;         __builtin_amdgcn_sched_barrier(0);
;         __syncthreads();
;         __builtin_amdgcn_sched_barrier(0);
;         const int g = lane >> 5, j32 = lane & 31;
; #pragma unroll
;         for (int ib = 0; ib < 4; ++ib) {
;             __builtin_amdgcn_sched_barrier(0);
;             u32x4 xv[4];
; #pragma unroll
;             for (int u = 0; u < 4; ++u) {
;                 const long row = (long)pm * 256 + (ib * 4 + u) * 16 + wid * 2 + g;
;                 xv[u] = *(const u32x4*)(xold + row * 1024 + pn * 256 + j32 * 8);
;             }
; #pragma unroll
;             for (int u = 0; u < 4; ++u) {
;                 const int rloc = (ib * 4 + u) * 16 + wid * 2 + g;
;                 const long row = (long)pm * 256 + rloc;
;                 const u32x4 a = *(const u32x4*)(lds + rloc * 528 + j32 * 16);
;                 u32x4 w; float ss = 0.f;
; #pragma unroll
;                 for (int e = 0; e < 4; ++e) {
;                     w[e] = pk2(bflo(xv[u][e]) + bflo(a[e]), bfhi(xv[u][e]) + bfhi(a[e]));
;                     const float b0 = bflo(w[e]), b1 = bfhi(w[e]);
;                     ss += b0 * b0 + b1 * b1;
;                 }
;                 *(u32x4*)(xnew + row * 1024 + pn * 256 + j32 * 8) = w;
; #pragma unroll
;                 for (int o = 1; o < 32; o <<= 1) ss += __shfl_xor(ss, o);
;                 if (j32 == 0) ssq[row * 4 + pn] = ss;
	v_cvt_pk_bf16_f32 v33, v34, v35
	v_cvt_pk_bf16_f32 v28, v28, v29
	v_cvt_pk_bf16_f32 v29, v30, v31
	v_cvt_pk_bf16_f32 v24, v24, v25
	v_cvt_pk_bf16_f32 v25, v26, v27
	v_add_u32_e32 v26, 0xc000, v138
	v_cvt_pk_bf16_f32 v20, v20, v21
	v_cvt_pk_bf16_f32 v21, v22, v23
	v_cvt_pk_bf16_f32 v16, v16, v17
	v_cvt_pk_bf16_f32 v17, v18, v19
	v_cvt_pk_bf16_f32 v12, v12, v13
	v_cvt_pk_bf16_f32 v13, v14, v15
	v_cvt_pk_bf16_f32 v8, v8, v9
	v_cvt_pk_bf16_f32 v9, v10, v11
	v_add_u32_e32 v10, 0xe000, v138
	v_cvt_pk_bf16_f32 v4, v4, v5
	v_cvt_pk_bf16_f32 v5, v6, v7
	v_cvt_pk_bf16_f32 v0, v0, v1
	v_cvt_pk_bf16_f32 v1, v2, v3
	ds_write2_b64 v138, v[124:125], v[120:121] offset1:4
	ds_write2_b64 v138, v[116:117], v[112:113] offset0:8 offset1:12
	ds_write2_b64 v106, v[108:109], v[104:105] offset0:32 offset1:36
	ds_write2_b64 v106, v[100:101], v[96:97] offset0:40 offset1:44
	ds_write2_b64 v90, v[92:93], v[88:89] offset0:64 offset1:68
	ds_write2_b64 v90, v[84:85], v[80:81] offset0:72 offset1:76
	ds_write2_b64 v74, v[76:77], v[72:73] offset0:96 offset1:100
	ds_write2_b64 v74, v[68:69], v[64:65] offset0:104 offset1:108
	ds_write2_b64 v58, v[60:61], v[56:57] offset0:128 offset1:132
	ds_write2_b64 v58, v[52:53], v[48:49] offset0:136 offset1:140
	ds_write2_b64 v42, v[44:45], v[40:41] offset0:160 offset1:164
	ds_write2_b64 v42, v[36:37], v[32:33] offset0:168 offset1:172
	ds_write2_b64 v26, v[28:29], v[24:25] offset0:192 offset1:196
	ds_write2_b64 v26, v[20:21], v[16:17] offset0:200 offset1:204
	ds_write2_b64 v10, v[12:13], v[8:9] offset0:224 offset1:228
	ds_write2_b64 v10, v[4:5], v[0:1] offset0:232 offset1:236
	s_waitcnt lgkmcnt(0)
	s_barrier
	v_ashrrev_i32_e32 v0, 5, v137
	v_ashrrev_i32_e32 v1, 5, v136
	v_and_b32_e32 v14, 31, v137
	v_and_b32_e32 v2, -2, v1
	v_ashrrev_i32_e32 v1, 31, v0
	v_ashrrev_i32_e32 v3, 31, v2
	v_lshl_add_u64 v[4:5], s[12:13], 0, v[0:1]
	s_lshl_b32 s16, s6, 8
	v_add_u32_e32 v16, v2, v0
	v_lshlrev_b32_e32 v146, 4, v14
	v_and_b32_e32 v0, 64, v169
	v_lshl_add_u64 v[4:5], v[4:5], 0, v[2:3]
	s_ashr_i32 s17, s16, 31
	v_add_u32_e32 v26, 0, v146
	v_add_u32_e32 v15, 64, v0
	v_cmp_eq_u32_e64 s[4:5], 0, v14
	v_cmp_eq_u32_e64 s[98:99], 16, v14
	s_lshl_b64 s[18:19], s[16:17], 1
	s_add_u32 s22, s68, s18
	s_addc_u32 s23, s69, s19
	v_lshl_add_u64 v[0:1], s[22:23], 0, v[146:147]
	v_lshlrev_b64 v[2:3], 11, v[4:5]
	v_lshl_add_u64 v[18:19], v[0:1], 0, v[2:3]
	flat_load_dwordx4 v[22:25], v[18:19]
	v_add_co_u32_e32 v0, vcc, s49, v18
	v_mul_lo_u32 v20, v16, s3
	s_nop 0
	v_addc_co_u32_e32 v1, vcc, 0, v19, vcc
	flat_load_dwordx4 v[8:11], v[0:1]
	v_add_co_u32_e32 v0, vcc, s48, v18
	v_add_u32_e32 v12, v26, v20
	s_nop 0
	v_addc_co_u32_e32 v1, vcc, 0, v19, vcc
	flat_load_dwordx4 v[4:7], v[0:1]
	v_add_co_u32_e32 v0, vcc, s47, v18
	ds_read_b128 v[28:31], v12
	s_nop 0
	v_addc_co_u32_e32 v1, vcc, 0, v19, vcc
	flat_load_dwordx4 v[0:3], v[0:1]
	v_ashrrev_i32_e32 v17, 31, v16
	s_waitcnt lgkmcnt(0)
	v_lshlrev_b32_e32 v32, 16, v28
	v_and_b32_e32 v33, 0xffff0000, v28
	v_lshlrev_b32_e32 v28, 16, v29
	v_and_b32_e32 v29, 0xffff0000, v29
	s_waitcnt vmcnt(0)
	v_lshlrev_b32_e32 v12, 16, v22
	v_and_b32_e32 v13, 0xffff0000, v22
	v_pk_add_f32 v[12:13], v[12:13], v[32:33]
	s_nop 0
	v_cvt_pk_bf16_f32 v22, v12, v13
	v_and_b32_e32 v13, 0xffff0000, v22
	v_lshlrev_b32_e32 v12, 16, v22
	v_mul_f32_e32 v21, v13, v13
	v_fmac_f32_e32 v21, v12, v12
	v_lshlrev_b32_e32 v12, 16, v23
	v_and_b32_e32 v13, 0xffff0000, v23
	v_pk_add_f32 v[12:13], v[12:13], v[28:29]
	v_lshlrev_b32_e32 v28, 16, v30
	v_cvt_pk_bf16_f32 v23, v12, v13
	v_and_b32_e32 v13, 0xffff0000, v23
	v_lshlrev_b32_e32 v12, 16, v23
	v_mul_f32_e32 v13, v13, v13
	v_fmac_f32_e32 v13, v12, v12
	v_add_f32_e32 v21, v21, v13
	v_lshlrev_b32_e32 v12, 16, v24
	v_and_b32_e32 v13, 0xffff0000, v24
	v_and_b32_e32 v29, 0xffff0000, v30
	v_pk_add_f32 v[12:13], v[12:13], v[28:29]
	v_lshlrev_b32_e32 v28, 16, v31
	v_cvt_pk_bf16_f32 v24, v12, v13
	v_and_b32_e32 v13, 0xffff0000, v24
	v_lshlrev_b32_e32 v12, 16, v24
	v_mul_f32_e32 v13, v13, v13
	v_fmac_f32_e32 v13, v12, v12
	v_add_f32_e32 v21, v13, v21
	v_lshlrev_b32_e32 v12, 16, v25
	v_and_b32_e32 v13, 0xffff0000, v25
	v_and_b32_e32 v29, 0xffff0000, v31
	v_pk_add_f32 v[12:13], v[12:13], v[28:29]
	s_nop 0
	v_cvt_pk_bf16_f32 v25, v12, v13
	v_and_b32_e32 v13, 0xffff0000, v25
	v_lshlrev_b32_e32 v12, 16, v25
	v_mul_f32_e32 v13, v13, v13
	v_fmac_f32_e32 v13, v12, v12
	v_add_f32_e32 v21, v13, v21
	v_lshl_add_u64 v[12:13], s[12:13], 0, v[16:17]
	v_lshlrev_b64 v[28:29], 11, v[12:13]
	v_xor_b32_e32 v17, 1, v169
	v_lshl_add_u64 v[28:29], s[10:11], 0, v[28:29]
	v_cmp_lt_i32_e32 vcc, v17, v15
	v_lshl_add_u64 v[28:29], v[28:29], 0, s[18:19]
	v_lshl_add_u64 v[28:29], v[28:29], 0, v[146:147]
	v_cndmask_b32_e32 v17, v169, v17, vcc
	v_lshlrev_b32_e32 v17, 2, v17
	flat_store_dwordx4 v[28:29], v[22:25]
	s_nop 1
	v_add_f32_dpp v86, v21, v21 quad_perm:[1,0,3,2] row_mask:0xf bank_mask:0xf
	s_nop 1
	v_add_f32_dpp v86, v86, v86 quad_perm:[2,3,0,1] row_mask:0xf bank_mask:0xf
	s_nop 1
	v_add_f32_dpp v86, v86, v86 row_half_mirror row_mask:0xf bank_mask:0xf
	s_nop 1
	v_add_f32_dpp v86, v86, v86 row_mirror row_mask:0xf bank_mask:0xf
	s_nop 1
	v_add_f32_dpp v86, v86, v86 row_bcast:15 row_mask:0xa bank_mask:0xf
	s_waitcnt lgkmcnt(0)
	v_xor_b32_e32 v22, 2, v169
	v_cmp_lt_i32_e32 vcc, v22, v15
	s_nop 1
	v_cndmask_b32_e32 v22, v169, v22, vcc
	v_lshlrev_b32_e32 v22, 2, v22
	s_waitcnt lgkmcnt(0)
	v_xor_b32_e32 v23, 4, v169
	v_cmp_lt_i32_e32 vcc, v23, v15
	s_nop 1
	v_cndmask_b32_e32 v23, v169, v23, vcc
	v_lshlrev_b32_e32 v23, 2, v23
	s_waitcnt lgkmcnt(0)
	v_xor_b32_e32 v24, 8, v169
	v_cmp_lt_i32_e32 vcc, v24, v15
	s_nop 1
	v_cndmask_b32_e32 v24, v169, v24, vcc
	v_lshlrev_b32_e32 v24, 2, v24
	s_waitcnt lgkmcnt(0)
	v_xor_b32_e32 v25, 16, v169
	v_cmp_lt_i32_e32 vcc, v25, v15
	s_nop 1
	v_cndmask_b32_e32 v15, v169, v25, vcc
	v_lshlrev_b32_e32 v25, 2, v15
	s_and_saveexec_b64 s[18:19], s[98:99]
	s_cbranch_execz .LBB0_778
	v_lshl_add_u64 v[12:13], v[12:13], 4, s[78:79]
	v_lshl_add_u64 v[12:13], s[6:7], 2, v[12:13]
	s_waitcnt lgkmcnt(0)
	v_mov_b32_e32 v15, v86
	flat_store_dword v[12:13], v15
